# all four GEMM K-loops 4-phase (first-iteration counted wait without clobbering vcc); plus conv row pipelining, hg_out LDS read-ahead, log-gate epilogue trimmed
# baseline (speedup 1.0000x reference)
; __device__ __forceinline__ int otid() { int t = threadIdx.x; asm volatile("" : "+v"(t)); return t; }
; #define PG8_STAGE(bufoff, gbase, voff) do { _Pragma("unroll") for (int _i = 0; _i < 2; ++_i) \
;     __builtin_amdgcn_global_load_lds((const unsigned*)((const char*)(gbase) + (voff)[_i]), (LAS unsigned*)(lds + (bufoff) + ldsw + _i * 8192), 16, 0, 0); } while (0)
; #define PG8_WAIT_V(n) asm volatile("s_waitcnt vmcnt(" #n ")" ::: "memory")
; #define PG8_BAR __builtin_amdgcn_s_barrier()
; template <class Epi, bool HOOK>
; __device__ __forceinline__ void gemm_phase(LAS unsigned char* lds, const Gemm g, const StaticOrder& S, const Epi& E, const int hook_t) {
;   const int tid = otid(), wid = __builtin_amdgcn_readfirstlane(tid >> 6), lane = tid & 63, wr = wid >> 2, wc = wid & 3, fr = lane & 15, fq = lane >> 4;
;   const int K = g.K, nt = K / BK;
;   unsigned voffA[2], voffB[2];
; #pragma unroll
;   for (int i = 0; i < 2; ++i) { int R, C; stage_rc(tid * 16 + i * 8192, R, C);
;     voffA[i] = (unsigned)(R * g.lda + C) * 2u; voffB[i] = (unsigned)(R * g.ldb + C) * 2u; }
;   const size_t kstep = (size_t)(BK * 2);
;   const size_t hstepA = (size_t)HALF * g.lda * 2, hstepB = (size_t)HALF * g.ldb * 2;
;   const size_t tstepA = 2 * hstepA, tstepB = 2 * hstepB;
;   const unsigned ldsw = (unsigned)wid * 1024u;
;   const int aoff = lds_byte(wr * 64 + fr, fq * 8), boff = lds_byte(wc * 32 + fr, fq * 8);
;     ...
;   const char* cA = (const char*)g.A + (size_t)cur.pm * tstepA; const char* cB = (const char*)g.Bt + (size_t)cur.pn * tstepB;
;   PG8_STAGE(PG8_SB(0, 0), cB, voffB); PG8_STAGE(PG8_SA(0, 0), cA, voffA); PG8_STAGE(PG8_SB(0, 1), cB + hstepB, voffB); PG8_STAGE(PG8_SA(0, 1), cA + hstepA, voffA);
;   if (wr == 1) PG8_BAR;
;   PG8_WAIT_V(4); PG8_BAR;
;   PG8_STAGE(PG8_SB(1, 0), cB + kstep, voffB); PG8_STAGE(PG8_SA(1, 0), cA + kstep, voffA); PG8_STAGE(PG8_SB(1, 1), cB + hstepB + kstep, voffB);
;   PG8_WAIT_V(6); PG8_BAR;
.LBB0_46:
	v_lshrrev_b32_e32 v20, 1, v18
	v_and_b32_e32 v20, 24, v20
	v_and_b32_e32 v19, 15, v18
	v_lshlrev_b32_e32 v21, 1, v20
	v_lshlrev_b32_e32 v18, 2, v18
	s_sext_i32_i8 s18, s0
	v_lshl_or_b32 v156, s1, 6, v19
	v_lshl_or_b32 v19, v19, 6, v21
	s_lshl_b32 s0, s1, 13
	v_and_b32_e32 v18, 32, v18
	v_bitop3_b32 v21, v19, s0, v18 bitop3:0xde
	s_lshl_b32 s0, s4, 5
	s_and_b32 s4, s0, 0x60
	s_add_i32 m0, s28, 0x18000
	v_lshl_add_u64 v[8:9], v[8:9], 0, s[56:57]
	s_lshl_b32 s0, s4, 7
	s_waitcnt vmcnt(2)
	s_barrier
	global_load_lds_dwordx4 v[8:9], off
	v_lshl_add_u64 v[6:7], v[6:7], 0, s[56:57]
	s_add_i32 m0, s28, 0x1a000
	s_add_i32 s34, s28, 0x8000
	s_add_i32 s35, s28, 0xa000
	v_bitop3_b32 v157, v19, s0, v18 bitop3:0xde
	global_load_lds_dwordx4 v[6:7], off
	v_lshl_add_u64 v[4:5], v[4:5], 0, s[56:57]
	s_mov_b32 m0, s34
	s_add_u32 s0, s16, 0x50080
	global_load_lds_dwordx4 v[4:5], off
	v_lshl_add_u64 v[2:3], v[2:3], 0, s[56:57]
	s_mov_b32 m0, s35
	s_addc_u32 s1, s17, 0
	global_load_lds_dwordx4 v[2:3], off
	s_add_i32 m0, s28, 0x1c000
	v_lshl_add_u64 v[2:3], s[0:1], 0, v[0:1]
	global_load_lds_dwordx4 v[2:3], off
	v_lshl_add_u64 v[2:3], s[0:1], 0, v[130:131]
	s_add_i32 m0, s28, 0x1e000
	v_readlane_b32 s0, v252, 31
	global_load_lds_dwordx4 v[2:3], off
	v_or_b32_e32 v158, s4, v20
	s_movk_i32 s4, 0x500
	v_readlane_b32 s1, v252, 32
	v_lshrrev_b32_e32 v3, 1, v10
	v_mul_lo_u32 v2, v12, s4
	s_movk_i32 s5, 0x5000
	s_and_b64 s[0:1], s[0:1], exec
	v_mad_u64_u32 v[2:3], s[0:1], v3, s5, v[2:3]
	v_or_b32_e32 v2, v2, v11
	v_add_lshl_u32 v132, v2, v13, 1
	v_lshrrev_b32_e32 v3, 1, v14
	v_mul_lo_u32 v2, v16, s4
	s_waitcnt vmcnt(6)
	v_mad_u64_u32 v[2:3], s[0:1], v3, s5, v[2:3]
	v_or_b32_e32 v2, v2, v15
	s_cselect_b32 s36, 5, 6
	v_mov_b32_e32 v133, v1
	v_add_lshl_u32 v134, v2, v17, 1
	v_mov_b32_e32 v135, v1
	s_mov_b32 s37, 0
	v_add_u32_e32 v159, 0, v21
	s_barrier
	s_branch .LBB0_48

; #define PG8_STAGE(bufoff, gbase, voff) do { _Pragma("unroll") for (int _i = 0; _i < 2; ++_i) \
;     __builtin_amdgcn_global_load_lds((const unsigned*)((const char*)(gbase) + (voff)[_i]), (LAS unsigned*)(lds + (bufoff) + ldsw + _i * 8192), 16, 0, 0); } while (0)
; #define PG8_LDA(dst, b, h) do { _Pragma("unroll") for (int m = 0; m < 4; ++m) _Pragma("unroll") for (int k = 0; k < 2; ++k) dst[m][k] = *(const LAS bf16x8*)(lds + PG8_SA(b, h) + aoff + m * 2048 + k * 1024); } while (0)
; #define PG8_LDB(dst, b, h) do { _Pragma("unroll") for (int n = 0; n < 2; ++n) _Pragma("unroll") for (int k = 0; k < 2; ++k) dst[n][k] = *(const LAS bf16x8*)(lds + PG8_SB(b, h) + boff + n * 2048 + k * 1024); } while (0)
; #define PG8_MMA(ai, bj, At, Bt) do { __builtin_amdgcn_s_setprio(1); _Pragma("unroll") for (int m = 0; m < 4; ++m) _Pragma("unroll") for (int n = 0; n < 2; ++n) _Pragma("unroll") for (int k = 0; k < 2; ++k) \
;     acc[ai][bj][m][n] = __builtin_amdgcn_mfma_f32_16x16x32_bf16(Bt[n][k], At[m][k], acc[ai][bj][m][n], 0, 0, 0); __builtin_amdgcn_s_setprio(0); } while (0)
; #define PG8_WAIT_L(n) asm volatile("s_waitcnt lgkmcnt(" #n ")" ::: "memory")
; #define PG8_BAR __builtin_amdgcn_s_barrier()
; #define PG8_SCHED __builtin_amdgcn_sched_barrier(0)
; template <class Epi, bool HOOK>
; __device__ __forceinline__ void gemm_phase(LAS unsigned char* lds, const Gemm g, const StaticOrder& S, const Epi& E, const int hook_t) {
;     ...
;     const char* nA = has_next ? (const char*)g.A + (size_t)nxt.pm * tstepA : cA; const char* nB = has_next ? (const char*)g.Bt + (size_t)nxt.pn * tstepB : cB;
;     for (int t = 0; t < nt; t += 2) {
;       const bool last = (t == nt - 2);
;       const char* a1 = cA + (size_t)(t + 1) * kstep;
;       const char* a2 = last ? nA : cA + (size_t)(t + 2) * kstep; const char* b2 = last ? nB : cB + (size_t)(t + 2) * kstep;
;       const char* a3 = a2 + kstep; const char* b3 = b2 + kstep;
;       if (HOOK) { if (t == hook_t) E.hook(acc, cur.pm, cur.pn, wr, wc, fr, fq); }
;       PG8_LDB(B0, 0, 0); PG8_SCHED; PG8_LDA(At, 0, 0); PG8_STAGE(PG8_SA(1, 1), a1 + hstepA, voffA);
;       PG8_WAIT_L(8); PG8_BAR; PG8_WAIT_L(0); PG8_MMA(0, 0, At, B0); PG8_BAR; PG8_SCHED;
;       PG8_LDB(B1, 0, 1); PG8_STAGE(PG8_SB(0, 0), b2, voffB);
;       PG8_BAR; PG8_WAIT_L(0); PG8_MMA(0, 1, At, B1); PG8_BAR;
.LBB0_59:
	s_add_u32 s18, s14, s16
	s_addc_u32 s19, s15, s17
	s_add_u32 s18, s18, 0x100
	s_addc_u32 s19, s19, 0
	s_add_u32 s42, s3, s16
	s_addc_u32 s43, s40, s17
	s_cmpk_eq_i32 s16, 0x900
	s_cselect_b32 s21, s1, s19
	s_cselect_b32 s20, s0, s18
	s_cselect_b32 s19, s7, s43
	s_cselect_b32 s18, s6, s42
	s_add_i32 s42, 0, 0x10000
	v_add_u32_e32 v168, s42, v157
	ds_read_b128 v[160:163], v168
	ds_read_b128 v[164:167], v168 offset:1024
	ds_read_b128 v[190:193], v168 offset:2048
	ds_read_b128 v[194:197], v168 offset:3072
	v_lshl_add_u64 v[168:169], v[152:153], 0, s[16:17]
	s_add_i32 m0, s28, 0xc000
	ds_read_b128 v[198:201], v159
	ds_read_b128 v[202:205], v159 offset:1024
	ds_read_b128 v[206:209], v159 offset:2048
	ds_read_b128 v[210:213], v159 offset:3072
	ds_read_b128 v[214:217], v159 offset:4096
	ds_read_b128 v[218:221], v159 offset:5120
	ds_read_b128 v[222:225], v159 offset:6144
	ds_read_b128 v[226:229], v159 offset:7168
	global_load_lds_dwordx4 v[168:169], off
	v_lshl_add_u64 v[168:169], v[154:155], 0, s[16:17]
	s_add_i32 m0, s28, 0xe000
	s_nop 0
	global_load_lds_dwordx4 v[168:169], off
	s_add_i32 s44, 0, 0x14000
	v_add_u32_e32 v168, s44, v157
	s_add_i32 s42, s42, s27
	ds_read_b128 v[230:233], v168
	ds_read_b128 v[234:237], v168 offset:1024
	ds_read_b128 v[238:241], v168 offset:2048
	ds_read_b128 v[242:245], v168 offset:3072
	s_cmp_eq_u32 s41, -2
	s_cbranch_scc0 .Lple_a0_strict
	s_cmp_gt_u32 s37, 1
	s_cbranch_scc1 .Lple_a0_relaxed
.Lple_a0_strict:
	s_waitcnt vmcnt(8) lgkmcnt(0)
	s_branch .Lple_a0_go

; #define PG8_STAGE(bufoff, gbase, voff) do { _Pragma("unroll") for (int _i = 0; _i < 2; ++_i) \
;     __builtin_amdgcn_global_load_lds((const unsigned*)((const char*)(gbase) + (voff)[_i]), (LAS unsigned*)(lds + (bufoff) + ldsw + _i * 8192), 16, 0, 0); } while (0)
; #define PG8_LDA(dst, b, h) do { _Pragma("unroll") for (int m = 0; m < 4; ++m) _Pragma("unroll") for (int k = 0; k < 2; ++k) dst[m][k] = *(const LAS bf16x8*)(lds + PG8_SA(b, h) + aoff + m * 2048 + k * 1024); } while (0)
; #define PG8_LDB(dst, b, h) do { _Pragma("unroll") for (int n = 0; n < 2; ++n) _Pragma("unroll") for (int k = 0; k < 2; ++k) dst[n][k] = *(const LAS bf16x8*)(lds + PG8_SB(b, h) + boff + n * 2048 + k * 1024); } while (0)
; #define PG8_MMA(ai, bj, At, Bt) do { __builtin_amdgcn_s_setprio(1); _Pragma("unroll") for (int m = 0; m < 4; ++m) _Pragma("unroll") for (int n = 0; n < 2; ++n) _Pragma("unroll") for (int k = 0; k < 2; ++k) \
;     acc[ai][bj][m][n] = __builtin_amdgcn_mfma_f32_16x16x32_bf16(Bt[n][k], At[m][k], acc[ai][bj][m][n], 0, 0, 0); __builtin_amdgcn_s_setprio(0); } while (0)
; #define PG8_WAIT_V(n) asm volatile("s_waitcnt vmcnt(" #n ")" ::: "memory")
; #define PG8_WAIT_L(n) asm volatile("s_waitcnt lgkmcnt(" #n ")" ::: "memory")
; #define PG8_BAR __builtin_amdgcn_s_barrier()
; #define PG8_SCHED __builtin_amdgcn_sched_barrier(0)
; template <class Epi, bool HOOK>
; __device__ __forceinline__ void gemm_phase(LAS unsigned char* lds, const Gemm g, const StaticOrder& S, const Epi& E, const int hook_t) {
;     ...
;       PG8_WAIT_L(8); PG8_BAR; PG8_WAIT_L(0); PG8_MMA(0, 0, At, B0); PG8_BAR; PG8_SCHED;
;       PG8_LDB(B1, 0, 1); PG8_STAGE(PG8_SB(0, 0), b2, voffB);
;       PG8_BAR; PG8_WAIT_L(0); PG8_MMA(0, 1, At, B1); PG8_BAR;
;       PG8_LDA(At, 0, 1); PG8_STAGE(PG8_SA(0, 0), a2, voffA);
;       PG8_BAR; PG8_WAIT_L(0); PG8_MMA(1, 0, At, B0); PG8_BAR; PG8_SCHED;
;       PG8_STAGE(PG8_SB(0, 1), b2 + hstepB, voffB);
;       PG8_WAIT_V(6); PG8_BAR; PG8_MMA(1, 1, At, B1); PG8_BAR;
.Lple_a0_go:
	s_barrier
	s_setprio 1
	v_mfma_f32_16x16x32_bf16 v[126:129], v[160:163], v[198:201], v[126:129]
	v_mfma_f32_16x16x32_bf16 v[122:125], v[190:193], v[198:201], v[122:125]
	v_mfma_f32_16x16x32_bf16 v[110:113], v[160:163], v[206:209], v[110:113]
	v_mfma_f32_16x16x32_bf16 v[106:109], v[190:193], v[206:209], v[106:109]
	v_mfma_f32_16x16x32_bf16 v[94:97], v[160:163], v[214:217], v[94:97]
	v_mfma_f32_16x16x32_bf16 v[90:93], v[190:193], v[214:217], v[90:93]
	v_mfma_f32_16x16x32_bf16 v[78:81], v[160:163], v[222:225], v[78:81]
	v_mfma_f32_16x16x32_bf16 v[74:77], v[190:193], v[222:225], v[74:77]
	v_mfma_f32_16x16x32_bf16 v[126:129], v[164:167], v[202:205], v[126:129]
	v_mfma_f32_16x16x32_bf16 v[122:125], v[194:197], v[202:205], v[122:125]
	v_mfma_f32_16x16x32_bf16 v[110:113], v[164:167], v[210:213], v[110:113]
	v_mfma_f32_16x16x32_bf16 v[106:109], v[194:197], v[210:213], v[106:109]
	v_mfma_f32_16x16x32_bf16 v[94:97], v[164:167], v[218:221], v[94:97]
	v_mfma_f32_16x16x32_bf16 v[90:93], v[194:197], v[218:221], v[90:93]
	v_mfma_f32_16x16x32_bf16 v[78:81], v[164:167], v[226:229], v[78:81]
	v_mfma_f32_16x16x32_bf16 v[74:77], v[194:197], v[226:229], v[74:77]
	v_mfma_f32_16x16x32_bf16 v[118:121], v[230:233], v[198:201], v[118:121]
	v_mfma_f32_16x16x32_bf16 v[114:117], v[238:241], v[198:201], v[114:117]
	v_mfma_f32_16x16x32_bf16 v[102:105], v[230:233], v[206:209], v[102:105]
	v_mfma_f32_16x16x32_bf16 v[98:101], v[238:241], v[206:209], v[98:101]
	v_mfma_f32_16x16x32_bf16 v[86:89], v[230:233], v[214:217], v[86:89]
	v_mfma_f32_16x16x32_bf16 v[82:85], v[238:241], v[214:217], v[82:85]
	v_mfma_f32_16x16x32_bf16 v[70:73], v[230:233], v[222:225], v[70:73]
	v_mfma_f32_16x16x32_bf16 v[66:69], v[238:241], v[222:225], v[66:69]
	v_mfma_f32_16x16x32_bf16 v[118:121], v[234:237], v[202:205], v[118:121]
	v_mfma_f32_16x16x32_bf16 v[114:117], v[242:245], v[202:205], v[114:117]
	v_mfma_f32_16x16x32_bf16 v[102:105], v[234:237], v[210:213], v[102:105]
	v_mfma_f32_16x16x32_bf16 v[98:101], v[242:245], v[210:213], v[98:101]
	v_mfma_f32_16x16x32_bf16 v[86:89], v[234:237], v[218:221], v[86:89]
	v_mfma_f32_16x16x32_bf16 v[82:85], v[242:245], v[218:221], v[82:85]
	v_mfma_f32_16x16x32_bf16 v[70:73], v[234:237], v[226:229], v[70:73]
	v_mfma_f32_16x16x32_bf16 v[66:69], v[242:245], v[226:229], v[66:69]
	s_setprio 0
	s_barrier
	ds_read_b128 v[198:201], v159 offset:16384
	ds_read_b128 v[202:205], v159 offset:17408
	ds_read_b128 v[206:209], v159 offset:18432
	ds_read_b128 v[210:213], v159 offset:19456
	ds_read_b128 v[214:217], v159 offset:20480
	ds_read_b128 v[218:221], v159 offset:21504
	ds_read_b128 v[222:225], v159 offset:22528
	ds_read_b128 v[226:229], v159 offset:23552
	v_lshl_add_u64 v[168:169], s[18:19], 0, v[0:1]
	s_mov_b32 m0, s42
	v_lshl_add_u64 v[246:247], s[18:19], 0, v[130:131]
	global_load_lds_dwordx4 v[168:169], off
	s_add_i32 m0, s42, 0x2000
	s_nop 0
	global_load_lds_dwordx4 v[246:247], off
	s_mov_b32 m0, s28
	v_lshl_add_u64 v[248:249], s[20:21], 0, v[0:1]
	global_load_lds_dwordx4 v[248:249], off
	v_lshl_add_u64 v[250:251], s[20:21], 0, v[130:131]
	s_mov_b32 m0, s29
	s_nop 0
	global_load_lds_dwordx4 v[250:251], off
	s_add_u32 s42, s18, 0x50000
	s_addc_u32 s43, s19, 0
	s_add_i32 s44, s44, s27
	v_lshl_add_u64 v[168:169], s[42:43], 0, v[0:1]
	s_mov_b32 m0, s44
	s_nop 0
	global_load_lds_dwordx4 v[168:169], off
	v_lshl_add_u64 v[168:169], s[42:43], 0, v[130:131]
	s_add_i32 m0, s44, 0x2000
	s_nop 0
	global_load_lds_dwordx4 v[168:169], off
	s_cmp_eq_u32 s41, -2
	s_cbranch_scc0 .Lple_b0_strict
	s_cmp_gt_u32 s37, 1
	s_cbranch_scc1 .Lple_b0_relaxed

; #define PG8_STAGE(bufoff, gbase, voff) do { _Pragma("unroll") for (int _i = 0; _i < 2; ++_i) \
;     __builtin_amdgcn_global_load_lds((const unsigned*)((const char*)(gbase) + (voff)[_i]), (LAS unsigned*)(lds + (bufoff) + ldsw + _i * 8192), 16, 0, 0); } while (0)
; #define PG8_LDA(dst, b, h) do { _Pragma("unroll") for (int m = 0; m < 4; ++m) _Pragma("unroll") for (int k = 0; k < 2; ++k) dst[m][k] = *(const LAS bf16x8*)(lds + PG8_SA(b, h) + aoff + m * 2048 + k * 1024); } while (0)
; #define PG8_LDB(dst, b, h) do { _Pragma("unroll") for (int n = 0; n < 2; ++n) _Pragma("unroll") for (int k = 0; k < 2; ++k) dst[n][k] = *(const LAS bf16x8*)(lds + PG8_SB(b, h) + boff + n * 2048 + k * 1024); } while (0)
; #define PG8_MMA(ai, bj, At, Bt) do { __builtin_amdgcn_s_setprio(1); _Pragma("unroll") for (int m = 0; m < 4; ++m) _Pragma("unroll") for (int n = 0; n < 2; ++n) _Pragma("unroll") for (int k = 0; k < 2; ++k) \
;     acc[ai][bj][m][n] = __builtin_amdgcn_mfma_f32_16x16x32_bf16(Bt[n][k], At[m][k], acc[ai][bj][m][n], 0, 0, 0); __builtin_amdgcn_s_setprio(0); } while (0)
; #define PG8_WAIT_V(n) asm volatile("s_waitcnt vmcnt(" #n ")" ::: "memory")
; #define PG8_WAIT_L(n) asm volatile("s_waitcnt lgkmcnt(" #n ")" ::: "memory")
; #define PG8_BAR __builtin_amdgcn_s_barrier()
; #define PG8_SCHED __builtin_amdgcn_sched_barrier(0)
; template <class Epi, bool HOOK>
; __device__ __forceinline__ void gemm_phase(LAS unsigned char* lds, const Gemm g, const StaticOrder& S, const Epi& E, const int hook_t) {
;     ...
;       PG8_BAR; PG8_WAIT_L(0); PG8_MMA(1, 0, At, B0); PG8_BAR; PG8_SCHED;
;       PG8_STAGE(PG8_SB(0, 1), b2 + hstepB, voffB);
;       PG8_WAIT_V(6); PG8_BAR; PG8_MMA(1, 1, At, B1); PG8_BAR;
;       PG8_LDB(B0, 1, 0); PG8_SCHED; PG8_LDA(At, 1, 0); PG8_STAGE(PG8_SA(0, 1), a2 + hstepA, voffA);
;       PG8_WAIT_L(8); PG8_BAR; PG8_WAIT_L(0); PG8_MMA(0, 0, At, B0); PG8_BAR; PG8_SCHED;
;       PG8_LDB(B1, 1, 1); PG8_STAGE(PG8_SB(1, 0), b3, voffB);
;       PG8_BAR; PG8_WAIT_L(0); PG8_MMA(0, 1, At, B1); PG8_BAR;
.Lple_b0_go:
	s_barrier
	s_setprio 1
	v_mfma_f32_16x16x32_bf16 v[62:65], v[160:163], v[198:201], v[62:65]
	v_mfma_f32_16x16x32_bf16 v[58:61], v[190:193], v[198:201], v[58:61]
	v_mfma_f32_16x16x32_bf16 v[46:49], v[160:163], v[206:209], v[46:49]
	v_mfma_f32_16x16x32_bf16 v[42:45], v[190:193], v[206:209], v[42:45]
	v_mfma_f32_16x16x32_bf16 v[30:33], v[160:163], v[214:217], v[30:33]
	v_mfma_f32_16x16x32_bf16 v[26:29], v[190:193], v[214:217], v[26:29]
	v_mfma_f32_16x16x32_bf16 v[14:17], v[160:163], v[222:225], v[14:17]
	v_mfma_f32_16x16x32_bf16 v[10:13], v[190:193], v[222:225], v[10:13]
	v_mfma_f32_16x16x32_bf16 v[62:65], v[164:167], v[202:205], v[62:65]
	v_mfma_f32_16x16x32_bf16 v[58:61], v[194:197], v[202:205], v[58:61]
	v_mfma_f32_16x16x32_bf16 v[46:49], v[164:167], v[210:213], v[46:49]
	v_mfma_f32_16x16x32_bf16 v[42:45], v[194:197], v[210:213], v[42:45]
	v_mfma_f32_16x16x32_bf16 v[30:33], v[164:167], v[218:221], v[30:33]
	v_mfma_f32_16x16x32_bf16 v[26:29], v[194:197], v[218:221], v[26:29]
	v_mfma_f32_16x16x32_bf16 v[14:17], v[164:167], v[226:229], v[14:17]
	v_mfma_f32_16x16x32_bf16 v[10:13], v[194:197], v[226:229], v[10:13]
	v_mfma_f32_16x16x32_bf16 v[54:57], v[230:233], v[198:201], v[54:57]
	v_mfma_f32_16x16x32_bf16 v[50:53], v[238:241], v[198:201], v[50:53]
	v_mfma_f32_16x16x32_bf16 v[38:41], v[230:233], v[206:209], v[38:41]
	v_mfma_f32_16x16x32_bf16 v[34:37], v[238:241], v[206:209], v[34:37]
	v_mfma_f32_16x16x32_bf16 v[22:25], v[230:233], v[214:217], v[22:25]
	v_mfma_f32_16x16x32_bf16 v[18:21], v[238:241], v[214:217], v[18:21]
	v_mfma_f32_16x16x32_bf16 v[6:9], v[230:233], v[222:225], v[6:9]
	v_mfma_f32_16x16x32_bf16 v[2:5], v[238:241], v[222:225], v[2:5]
	v_mfma_f32_16x16x32_bf16 v[54:57], v[234:237], v[202:205], v[54:57]
	v_mfma_f32_16x16x32_bf16 v[50:53], v[242:245], v[202:205], v[50:53]
	v_mfma_f32_16x16x32_bf16 v[38:41], v[234:237], v[210:213], v[38:41]
	v_mfma_f32_16x16x32_bf16 v[34:37], v[242:245], v[210:213], v[34:37]
	v_mfma_f32_16x16x32_bf16 v[22:25], v[234:237], v[218:221], v[22:25]
	v_mfma_f32_16x16x32_bf16 v[18:21], v[242:245], v[218:221], v[18:21]
	v_mfma_f32_16x16x32_bf16 v[6:9], v[234:237], v[226:229], v[6:9]
	v_mfma_f32_16x16x32_bf16 v[2:5], v[242:245], v[226:229], v[2:5]
	s_setprio 0
	s_add_i32 s42, 0, 0x18000
	v_add_u32_e32 v194, s42, v157
	s_barrier
	ds_read_b128 v[160:163], v194
	ds_read_b128 v[164:167], v194 offset:1024
	ds_read_b128 v[190:193], v194 offset:2048
	ds_read_b128 v[194:197], v194 offset:3072
	s_add_u32 s20, s20, 0x50000
	s_addc_u32 s21, s21, 0
	s_mov_b32 m0, s30
	v_lshl_add_u64 v[230:231], s[20:21], 0, v[0:1]
	ds_read_b128 v[198:201], v159 offset:32768
	ds_read_b128 v[202:205], v159 offset:33792
	ds_read_b128 v[206:209], v159 offset:34816
	ds_read_b128 v[210:213], v159 offset:35840
	ds_read_b128 v[214:217], v159 offset:36864
	ds_read_b128 v[218:221], v159 offset:37888
	ds_read_b128 v[222:225], v159 offset:38912
	ds_read_b128 v[226:229], v159 offset:39936
	global_load_lds_dwordx4 v[230:231], off
	v_lshl_add_u64 v[230:231], s[20:21], 0, v[130:131]
	s_mov_b32 m0, s31
	s_nop 0
	global_load_lds_dwordx4 v[230:231], off
	s_add_i32 s20, 0, 0x1c000
	s_add_i32 s21, s42, s27
	v_add_u32_e32 v242, s20, v157
	ds_read_b128 v[230:233], v242
	ds_read_b128 v[234:237], v242 offset:1024
	ds_read_b128 v[238:241], v242 offset:2048
	ds_read_b128 v[242:245], v242 offset:3072
	s_waitcnt vmcnt(8) lgkmcnt(0)
	s_barrier
	s_setprio 1
	v_mfma_f32_16x16x32_bf16 v[126:129], v[160:163], v[198:201], v[126:129]
	v_mfma_f32_16x16x32_bf16 v[122:125], v[190:193], v[198:201], v[122:125]
	v_mfma_f32_16x16x32_bf16 v[110:113], v[160:163], v[206:209], v[110:113]
	v_mfma_f32_16x16x32_bf16 v[106:109], v[190:193], v[206:209], v[106:109]
	v_mfma_f32_16x16x32_bf16 v[94:97], v[160:163], v[214:217], v[94:97]
	v_mfma_f32_16x16x32_bf16 v[90:93], v[190:193], v[214:217], v[90:93]
	v_mfma_f32_16x16x32_bf16 v[78:81], v[160:163], v[222:225], v[78:81]
	v_mfma_f32_16x16x32_bf16 v[74:77], v[190:193], v[222:225], v[74:77]
	v_mfma_f32_16x16x32_bf16 v[126:129], v[164:167], v[202:205], v[126:129]
	v_mfma_f32_16x16x32_bf16 v[122:125], v[194:197], v[202:205], v[122:125]
	v_mfma_f32_16x16x32_bf16 v[110:113], v[164:167], v[210:213], v[110:113]
	v_mfma_f32_16x16x32_bf16 v[106:109], v[194:197], v[210:213], v[106:109]
	v_mfma_f32_16x16x32_bf16 v[94:97], v[164:167], v[218:221], v[94:97]
	v_mfma_f32_16x16x32_bf16 v[90:93], v[194:197], v[218:221], v[90:93]
	v_mfma_f32_16x16x32_bf16 v[78:81], v[164:167], v[226:229], v[78:81]
	v_mfma_f32_16x16x32_bf16 v[74:77], v[194:197], v[226:229], v[74:77]
	v_mfma_f32_16x16x32_bf16 v[118:121], v[230:233], v[198:201], v[118:121]
	v_mfma_f32_16x16x32_bf16 v[114:117], v[238:241], v[198:201], v[114:117]
	v_mfma_f32_16x16x32_bf16 v[102:105], v[230:233], v[206:209], v[102:105]
	v_mfma_f32_16x16x32_bf16 v[98:101], v[238:241], v[206:209], v[98:101]
	v_mfma_f32_16x16x32_bf16 v[86:89], v[230:233], v[214:217], v[86:89]
	v_mfma_f32_16x16x32_bf16 v[82:85], v[238:241], v[214:217], v[82:85]
	v_mfma_f32_16x16x32_bf16 v[70:73], v[230:233], v[222:225], v[70:73]
	v_mfma_f32_16x16x32_bf16 v[66:69], v[238:241], v[222:225], v[66:69]
	v_mfma_f32_16x16x32_bf16 v[118:121], v[234:237], v[202:205], v[118:121]
	v_mfma_f32_16x16x32_bf16 v[114:117], v[242:245], v[202:205], v[114:117]
	v_mfma_f32_16x16x32_bf16 v[102:105], v[234:237], v[210:213], v[102:105]
	v_mfma_f32_16x16x32_bf16 v[98:101], v[242:245], v[210:213], v[98:101]
	v_mfma_f32_16x16x32_bf16 v[86:89], v[234:237], v[218:221], v[86:89]
	v_mfma_f32_16x16x32_bf16 v[82:85], v[242:245], v[218:221], v[82:85]
	v_mfma_f32_16x16x32_bf16 v[70:73], v[234:237], v[226:229], v[70:73]
	v_mfma_f32_16x16x32_bf16 v[66:69], v[242:245], v[226:229], v[66:69]
	s_setprio 0
	s_barrier
; #define PG8_STAGE(bufoff, gbase, voff) do { _Pragma("unroll") for (int _i = 0; _i < 2; ++_i) \
;     __builtin_amdgcn_global_load_lds((const unsigned*)((const char*)(gbase) + (voff)[_i]), (LAS unsigned*)(lds + (bufoff) + ldsw + _i * 8192), 16, 0, 0); } while (0)
; #define PG8_LDA(dst, b, h) do { _Pragma("unroll") for (int m = 0; m < 4; ++m) _Pragma("unroll") for (int k = 0; k < 2; ++k) dst[m][k] = *(const LAS bf16x8*)(lds + PG8_SA(b, h) + aoff + m * 2048 + k * 1024); } while (0)
; #define PG8_MMA(ai, bj, At, Bt) do { __builtin_amdgcn_s_setprio(1); _Pragma("unroll") for (int m = 0; m < 4; ++m) _Pragma("unroll") for (int n = 0; n < 2; ++n) _Pragma("unroll") for (int k = 0; k < 2; ++k) \
;     acc[ai][bj][m][n] = __builtin_amdgcn_mfma_f32_16x16x32_bf16(Bt[n][k], At[m][k], acc[ai][bj][m][n], 0, 0, 0); __builtin_amdgcn_s_setprio(0); } while (0)
; #define PG8_WAIT_V(n) asm volatile("s_waitcnt vmcnt(" #n ")" ::: "memory")
; #define PG8_WAIT_L(n) asm volatile("s_waitcnt lgkmcnt(" #n ")" ::: "memory")
; #define PG8_BAR __builtin_amdgcn_s_barrier()
; #define PG8_SCHED __builtin_amdgcn_sched_barrier(0)
; template <class Epi, bool HOOK>
; __device__ __forceinline__ void gemm_phase(LAS unsigned char* lds, const Gemm g, const StaticOrder& S, const Epi& E, const int hook_t) {
;     ...
;       PG8_LDA(At, 1, 1); PG8_STAGE(PG8_SA(1, 0), a3, voffA);
;       PG8_BAR; PG8_WAIT_L(0); PG8_MMA(1, 0, At, B0); PG8_BAR; PG8_SCHED;
;       PG8_STAGE(PG8_SB(1, 1), b3 + hstepB, voffB);
;       PG8_WAIT_V(6); PG8_BAR; PG8_MMA(1, 1, At, B1); PG8_BAR;
;     }
	ds_read_b128 v[198:201], v159 offset:49152
	ds_read_b128 v[202:205], v159 offset:50176
	ds_read_b128 v[206:209], v159 offset:51200
	ds_read_b128 v[210:213], v159 offset:52224
	ds_read_b128 v[214:217], v159 offset:53248
	ds_read_b128 v[218:221], v159 offset:54272
	ds_read_b128 v[222:225], v159 offset:55296
	ds_read_b128 v[226:229], v159 offset:56320
	s_mov_b32 m0, s21
	v_lshl_add_u64 v[168:169], s[18:19], 0, v[0:1]
	v_lshl_add_u64 v[168:169], v[168:169], 0, s[56:57]
	global_load_lds_dwordx4 v[168:169], off
	v_lshl_add_u64 v[168:169], v[246:247], 0, s[56:57]
	s_add_i32 m0, s21, 0x2000
	s_nop 0
	global_load_lds_dwordx4 v[168:169], off
	s_mov_b32 m0, s34
	v_lshl_add_u64 v[168:169], v[248:249], 0, s[56:57]
	global_load_lds_dwordx4 v[168:169], off
	v_lshl_add_u64 v[168:169], v[250:251], 0, s[56:57]
	s_mov_b32 m0, s35
	s_nop 0
	global_load_lds_dwordx4 v[168:169], off
	s_add_u32 s18, s18, 0x50080
	s_addc_u32 s19, s19, 0
	s_add_i32 s20, s20, s27
	v_lshl_add_u64 v[168:169], s[18:19], 0, v[0:1]
	s_mov_b32 m0, s20
	s_nop 0
	global_load_lds_dwordx4 v[168:169], off
	v_lshl_add_u64 v[168:169], s[18:19], 0, v[130:131]
	s_add_i32 m0, s20, 0x2000
	s_nop 0
	global_load_lds_dwordx4 v[168:169], off
	s_waitcnt vmcnt(8) lgkmcnt(0)
	s_barrier
	s_setprio 1
	v_mfma_f32_16x16x32_bf16 v[62:65], v[160:163], v[198:201], v[62:65]
	v_mfma_f32_16x16x32_bf16 v[58:61], v[190:193], v[198:201], v[58:61]
	v_mfma_f32_16x16x32_bf16 v[46:49], v[160:163], v[206:209], v[46:49]
	v_mfma_f32_16x16x32_bf16 v[42:45], v[190:193], v[206:209], v[42:45]
	v_mfma_f32_16x16x32_bf16 v[30:33], v[160:163], v[214:217], v[30:33]
	v_mfma_f32_16x16x32_bf16 v[26:29], v[190:193], v[214:217], v[26:29]
	v_mfma_f32_16x16x32_bf16 v[14:17], v[160:163], v[222:225], v[14:17]
	v_mfma_f32_16x16x32_bf16 v[10:13], v[190:193], v[222:225], v[10:13]
	v_mfma_f32_16x16x32_bf16 v[62:65], v[164:167], v[202:205], v[62:65]
	v_mfma_f32_16x16x32_bf16 v[58:61], v[194:197], v[202:205], v[58:61]
	v_mfma_f32_16x16x32_bf16 v[46:49], v[164:167], v[210:213], v[46:49]
	v_mfma_f32_16x16x32_bf16 v[42:45], v[194:197], v[210:213], v[42:45]
	v_mfma_f32_16x16x32_bf16 v[30:33], v[164:167], v[218:221], v[30:33]
	v_mfma_f32_16x16x32_bf16 v[26:29], v[194:197], v[218:221], v[26:29]
	v_mfma_f32_16x16x32_bf16 v[14:17], v[164:167], v[226:229], v[14:17]
	v_mfma_f32_16x16x32_bf16 v[10:13], v[194:197], v[226:229], v[10:13]
	v_mfma_f32_16x16x32_bf16 v[54:57], v[230:233], v[198:201], v[54:57]
	v_mfma_f32_16x16x32_bf16 v[50:53], v[238:241], v[198:201], v[50:53]
	v_mfma_f32_16x16x32_bf16 v[38:41], v[230:233], v[206:209], v[38:41]
	v_mfma_f32_16x16x32_bf16 v[34:37], v[238:241], v[206:209], v[34:37]
	v_mfma_f32_16x16x32_bf16 v[22:25], v[230:233], v[214:217], v[22:25]
	v_mfma_f32_16x16x32_bf16 v[18:21], v[238:241], v[214:217], v[18:21]
	v_mfma_f32_16x16x32_bf16 v[6:9], v[230:233], v[222:225], v[6:9]
	v_mfma_f32_16x16x32_bf16 v[2:5], v[238:241], v[222:225], v[2:5]
	v_mfma_f32_16x16x32_bf16 v[54:57], v[234:237], v[202:205], v[54:57]
	v_mfma_f32_16x16x32_bf16 v[50:53], v[242:245], v[202:205], v[50:53]
	v_mfma_f32_16x16x32_bf16 v[38:41], v[234:237], v[210:213], v[38:41]
	v_mfma_f32_16x16x32_bf16 v[34:37], v[242:245], v[210:213], v[34:37]
	v_mfma_f32_16x16x32_bf16 v[22:25], v[234:237], v[218:221], v[22:25]
	v_mfma_f32_16x16x32_bf16 v[18:21], v[242:245], v[218:221], v[18:21]
	v_mfma_f32_16x16x32_bf16 v[6:9], v[234:237], v[226:229], v[6:9]
	v_mfma_f32_16x16x32_bf16 v[2:5], v[242:245], v[226:229], v[2:5]
	s_setprio 0
	s_add_i32 s41, s41, 2
	s_add_u32 s16, s16, 0x100
	s_addc_u32 s17, s17, 0
	s_cmp_gt_u32 s41, 17
	s_barrier
	s_cbranch_scc1 .LBB0_47

; #define PG8_STAGE(bufoff, gbase, voff) do { _Pragma("unroll") for (int _i = 0; _i < 2; ++_i) \
;     __builtin_amdgcn_global_load_lds((const unsigned*)((const char*)(gbase) + (voff)[_i]), (LAS unsigned*)(lds + (bufoff) + ldsw + _i * 8192), 16, 0, 0); } while (0)
; #define PG8_LDA(dst, b, h) do { _Pragma("unroll") for (int m = 0; m < 4; ++m) _Pragma("unroll") for (int k = 0; k < 2; ++k) dst[m][k] = *(const LAS bf16x8*)(lds + PG8_SA(b, h) + aoff + m * 2048 + k * 1024); } while (0)
; #define PG8_LDB(dst, b, h) do { _Pragma("unroll") for (int n = 0; n < 2; ++n) _Pragma("unroll") for (int k = 0; k < 2; ++k) dst[n][k] = *(const LAS bf16x8*)(lds + PG8_SB(b, h) + boff + n * 2048 + k * 1024); } while (0)
; #define PG8_MMA(ai, bj, At, Bt) do { __builtin_amdgcn_s_setprio(1); _Pragma("unroll") for (int m = 0; m < 4; ++m) _Pragma("unroll") for (int n = 0; n < 2; ++n) _Pragma("unroll") for (int k = 0; k < 2; ++k) \
;     acc[ai][bj][m][n] = __builtin_amdgcn_mfma_f32_16x16x32_bf16(Bt[n][k], At[m][k], acc[ai][bj][m][n], 0, 0, 0); __builtin_amdgcn_s_setprio(0); } while (0)
; #define PG8_WAIT_L(n) asm volatile("s_waitcnt lgkmcnt(" #n ")" ::: "memory")
; #define PG8_BAR __builtin_amdgcn_s_barrier()
; #define PG8_SCHED __builtin_amdgcn_sched_barrier(0)
; template <class Epi, bool HOOK>
; __device__ __forceinline__ void gemm_phase(LAS unsigned char* lds, const Gemm g, const StaticOrder& S, const Epi& E, const int hook_t) {
;     ...
;       const bool last = (t == nt - 2);
;       const char* a1 = cA + (size_t)(t + 1) * kstep;
;       const char* a2 = last ? nA : cA + (size_t)(t + 2) * kstep; const char* b2 = last ? nB : cB + (size_t)(t + 2) * kstep;
;       const char* a3 = a2 + kstep; const char* b3 = b2 + kstep;
;       if (HOOK) { if (t == hook_t) E.hook(acc, cur.pm, cur.pn, wr, wc, fr, fq); }
;       PG8_LDB(B0, 0, 0); PG8_SCHED; PG8_LDA(At, 0, 0); PG8_STAGE(PG8_SA(1, 1), a1 + hstepA, voffA);
;       PG8_WAIT_L(8); PG8_BAR; PG8_WAIT_L(0); PG8_MMA(0, 0, At, B0); PG8_BAR; PG8_SCHED;
;       PG8_LDB(B1, 0, 1); PG8_STAGE(PG8_SB(0, 0), b2, voffB);
.LBB0_126:
	s_add_i32 s48, s18, 2
	s_add_u32 s20, s16, 0x80
	s_addc_u32 s19, s17, 0
	s_add_i32 s49, 0, 0x10000
	v_add_u32_e32 v152, s49, v137
	ds_read_b128 v[140:143], v152
	ds_read_b128 v[144:147], v152 offset:1024
	ds_read_b128 v[148:151], v152 offset:2048
	ds_read_b128 v[152:155], v152 offset:3072
	s_cmp_eq_u32 s41, s18
	s_cselect_b32 s18, s0, s20
	s_cselect_b32 s19, s1, s19
	s_cselect_b32 s21, s7, s47
	s_cselect_b32 s20, s6, s46
	v_lshl_add_u64 v[168:169], s[16:17], 0, v[132:133]
	s_add_i32 m0, s31, 0xc000
	ds_read_b128 v[156:159], v139
	ds_read_b128 v[160:163], v139 offset:1024
	ds_read_b128 v[164:167], v139 offset:2048
	ds_read_b128 v[190:193], v139 offset:3072
	ds_read_b128 v[194:197], v139 offset:4096
	ds_read_b128 v[198:201], v139 offset:5120
	ds_read_b128 v[202:205], v139 offset:6144
	ds_read_b128 v[206:209], v139 offset:7168
	global_load_lds_dwordx4 v[168:169], off
	v_lshl_add_u64 v[168:169], s[16:17], 0, v[134:135]
	s_add_i32 m0, s31, 0xe000
	s_nop 0
	global_load_lds_dwordx4 v[168:169], off
	s_add_i32 s52, 0, 0x14000
	v_add_u32_e32 v168, s52, v137
	s_add_i32 s49, s49, s26
	ds_read_b128 v[210:213], v168
	ds_read_b128 v[214:217], v168 offset:1024
	ds_read_b128 v[218:221], v168 offset:2048
	ds_read_b128 v[222:225], v168 offset:3072
	s_cmp_eq_u32 s48, 2
	s_cbranch_scc0 .Lpl_a0_strict
	s_cmp_gt_u32 s42, 1
	s_cbranch_scc1 .Lpl_a0_relaxed

; #define PG8_STAGE(bufoff, gbase, voff) do { _Pragma("unroll") for (int _i = 0; _i < 2; ++_i) \
;     __builtin_amdgcn_global_load_lds((const unsigned*)((const char*)(gbase) + (voff)[_i]), (LAS unsigned*)(lds + (bufoff) + ldsw + _i * 8192), 16, 0, 0); } while (0)
; #define PG8_LDA(dst, b, h) do { _Pragma("unroll") for (int m = 0; m < 4; ++m) _Pragma("unroll") for (int k = 0; k < 2; ++k) dst[m][k] = *(const LAS bf16x8*)(lds + PG8_SA(b, h) + aoff + m * 2048 + k * 1024); } while (0)
; #define PG8_LDB(dst, b, h) do { _Pragma("unroll") for (int n = 0; n < 2; ++n) _Pragma("unroll") for (int k = 0; k < 2; ++k) dst[n][k] = *(const LAS bf16x8*)(lds + PG8_SB(b, h) + boff + n * 2048 + k * 1024); } while (0)
; #define PG8_MMA(ai, bj, At, Bt) do { __builtin_amdgcn_s_setprio(1); _Pragma("unroll") for (int m = 0; m < 4; ++m) _Pragma("unroll") for (int n = 0; n < 2; ++n) _Pragma("unroll") for (int k = 0; k < 2; ++k) \
;     acc[ai][bj][m][n] = __builtin_amdgcn_mfma_f32_16x16x32_bf16(Bt[n][k], At[m][k], acc[ai][bj][m][n], 0, 0, 0); __builtin_amdgcn_s_setprio(0); } while (0)
; #define PG8_WAIT_L(n) asm volatile("s_waitcnt lgkmcnt(" #n ")" ::: "memory")
; #define PG8_BAR __builtin_amdgcn_s_barrier()
; #define PG8_SCHED __builtin_amdgcn_sched_barrier(0)
; template <class Epi, bool HOOK>
; __device__ __forceinline__ void gemm_phase(LAS unsigned char* lds, const Gemm g, const StaticOrder& S, const Epi& E, const int hook_t) {
;     ...
;       PG8_WAIT_L(8); PG8_BAR; PG8_WAIT_L(0); PG8_MMA(0, 0, At, B0); PG8_BAR; PG8_SCHED;
;       PG8_LDB(B1, 0, 1); PG8_STAGE(PG8_SB(0, 0), b2, voffB);
;       PG8_BAR; PG8_WAIT_L(0); PG8_MMA(0, 1, At, B1); PG8_BAR;
;       PG8_LDA(At, 0, 1); PG8_STAGE(PG8_SA(0, 0), a2, voffA);
;       PG8_BAR; PG8_WAIT_L(0); PG8_MMA(1, 0, At, B0); PG8_BAR; PG8_SCHED;
;       PG8_STAGE(PG8_SB(0, 1), b2 + hstepB, voffB);
.Lpl_a0_go:
	s_barrier
	s_setprio 1
	v_mfma_f32_16x16x32_bf16 v[126:129], v[140:143], v[156:159], v[126:129]
	v_mfma_f32_16x16x32_bf16 v[122:125], v[148:151], v[156:159], v[122:125]
	v_mfma_f32_16x16x32_bf16 v[118:121], v[140:143], v[164:167], v[118:121]
	v_mfma_f32_16x16x32_bf16 v[114:117], v[148:151], v[164:167], v[114:117]
	v_mfma_f32_16x16x32_bf16 v[102:105], v[140:143], v[194:197], v[102:105]
	v_mfma_f32_16x16x32_bf16 v[98:101], v[148:151], v[194:197], v[98:101]
	v_mfma_f32_16x16x32_bf16 v[86:89], v[140:143], v[202:205], v[86:89]
	v_mfma_f32_16x16x32_bf16 v[82:85], v[148:151], v[202:205], v[82:85]
	v_mfma_f32_16x16x32_bf16 v[126:129], v[144:147], v[160:163], v[126:129]
	v_mfma_f32_16x16x32_bf16 v[122:125], v[152:155], v[160:163], v[122:125]
	v_mfma_f32_16x16x32_bf16 v[118:121], v[144:147], v[190:193], v[118:121]
	v_mfma_f32_16x16x32_bf16 v[114:117], v[152:155], v[190:193], v[114:117]
	v_mfma_f32_16x16x32_bf16 v[102:105], v[144:147], v[198:201], v[102:105]
	v_mfma_f32_16x16x32_bf16 v[98:101], v[152:155], v[198:201], v[98:101]
	v_mfma_f32_16x16x32_bf16 v[86:89], v[144:147], v[206:209], v[86:89]
	v_mfma_f32_16x16x32_bf16 v[82:85], v[152:155], v[206:209], v[82:85]
	v_mfma_f32_16x16x32_bf16 v[110:113], v[210:213], v[156:159], v[110:113]
	v_mfma_f32_16x16x32_bf16 v[106:109], v[218:221], v[156:159], v[106:109]
	v_mfma_f32_16x16x32_bf16 v[94:97], v[210:213], v[164:167], v[94:97]
	v_mfma_f32_16x16x32_bf16 v[90:93], v[218:221], v[164:167], v[90:93]
	v_mfma_f32_16x16x32_bf16 v[78:81], v[210:213], v[194:197], v[78:81]
	v_mfma_f32_16x16x32_bf16 v[74:77], v[218:221], v[194:197], v[74:77]
	v_mfma_f32_16x16x32_bf16 v[70:73], v[210:213], v[202:205], v[70:73]
	v_mfma_f32_16x16x32_bf16 v[66:69], v[218:221], v[202:205], v[66:69]
	v_mfma_f32_16x16x32_bf16 v[110:113], v[214:217], v[160:163], v[110:113]
	v_mfma_f32_16x16x32_bf16 v[106:109], v[222:225], v[160:163], v[106:109]
	v_mfma_f32_16x16x32_bf16 v[94:97], v[214:217], v[190:193], v[94:97]
	v_mfma_f32_16x16x32_bf16 v[90:93], v[222:225], v[190:193], v[90:93]
	v_mfma_f32_16x16x32_bf16 v[78:81], v[214:217], v[198:201], v[78:81]
	v_mfma_f32_16x16x32_bf16 v[74:77], v[222:225], v[198:201], v[74:77]
	v_mfma_f32_16x16x32_bf16 v[70:73], v[214:217], v[206:209], v[70:73]
	v_mfma_f32_16x16x32_bf16 v[66:69], v[222:225], v[206:209], v[66:69]
	s_setprio 0
	s_barrier
	ds_read_b128 v[156:159], v139 offset:16384
	ds_read_b128 v[160:163], v139 offset:17408
	ds_read_b128 v[164:167], v139 offset:18432
	ds_read_b128 v[190:193], v139 offset:19456
	ds_read_b128 v[194:197], v139 offset:20480
	ds_read_b128 v[198:201], v139 offset:21504
	ds_read_b128 v[202:205], v139 offset:22528
	ds_read_b128 v[206:209], v139 offset:23552
	v_lshl_add_u64 v[168:169], s[20:21], 0, v[0:1]
	s_mov_b32 m0, s49
	v_lshl_add_u64 v[226:227], s[20:21], 0, v[130:131]
	global_load_lds_dwordx4 v[168:169], off
	s_add_i32 m0, s49, 0x2000
	s_nop 0
	global_load_lds_dwordx4 v[226:227], off
	s_mov_b32 m0, s31
	v_lshl_add_u64 v[228:229], s[18:19], 0, v[0:1]
	global_load_lds_dwordx4 v[228:229], off
	v_lshl_add_u64 v[230:231], s[18:19], 0, v[130:131]
	s_mov_b32 m0, s34
	s_nop 0
	global_load_lds_dwordx4 v[230:231], off
	s_add_u32 s20, s20, s50
	s_addc_u32 s21, s21, 0
	s_add_i32 s49, s52, s26
	v_lshl_add_u64 v[232:233], s[20:21], 0, v[0:1]
	s_mov_b32 m0, s49
	v_lshl_add_u64 v[234:235], s[20:21], 0, v[130:131]
	global_load_lds_dwordx4 v[232:233], off
	s_add_i32 m0, s49, 0x2000
	s_nop 0
	global_load_lds_dwordx4 v[234:235], off
	s_cmp_eq_u32 s48, 2
	s_cbranch_scc0 .Lpl_b0_strict
	s_cmp_gt_u32 s42, 1
	s_cbranch_scc1 .Lpl_b0_relaxed

; #define PG8_STAGE(bufoff, gbase, voff) do { _Pragma("unroll") for (int _i = 0; _i < 2; ++_i) \
;     __builtin_amdgcn_global_load_lds((const unsigned*)((const char*)(gbase) + (voff)[_i]), (LAS unsigned*)(lds + (bufoff) + ldsw + _i * 8192), 16, 0, 0); } while (0)
; #define PG8_WAIT_V(n) asm volatile("s_waitcnt vmcnt(" #n ")" ::: "memory")
; #define PG8_BAR __builtin_amdgcn_s_barrier()
; template <class Epi, bool HOOK>
; __device__ __forceinline__ void gemm_phase(LAS unsigned char* lds, const Gemm g, const StaticOrder& S, const Epi& E, const int hook_t) {
;     ...
;   for (int i = 0; i < 2; ++i) { int R, C; stage_rc(tid * 16 + i * 8192, R, C);
;     voffA[i] = (unsigned)(R * g.lda + C) * 2u; voffB[i] = (unsigned)(R * g.ldb + C) * 2u; }
;   const size_t kstep = (size_t)(BK * 2);
;   const size_t hstepA = (size_t)HALF * g.lda * 2, hstepB = (size_t)HALF * g.ldb * 2;
;   const size_t tstepA = 2 * hstepA, tstepB = 2 * hstepB;
;   const unsigned ldsw = (unsigned)wid * 1024u;
;   const int aoff = lds_byte(wr * 64 + fr, fq * 8), boff = lds_byte(wc * 32 + fr, fq * 8);
;     ...
;   PG8_STAGE(PG8_SB(0, 0), cB, voffB); PG8_STAGE(PG8_SA(0, 0), cA, voffA); PG8_STAGE(PG8_SB(0, 1), cB + hstepB, voffB); PG8_STAGE(PG8_SA(0, 1), cA + hstepA, voffA);
;   if (wr == 1) PG8_BAR;
;   PG8_WAIT_V(4); PG8_BAR;
;   PG8_STAGE(PG8_SB(1, 0), cB + kstep, voffB); PG8_STAGE(PG8_SA(1, 0), cA + kstep, voffA); PG8_STAGE(PG8_SB(1, 1), cB + hstepB + kstep, voffB);
;   PG8_WAIT_V(6); PG8_BAR;
.LBB0_140:
	s_sext_i32_i8 s17, s4
	v_and_b32_e32 v16, 48, v15
	v_lshlrev_b32_e32 v17, 6, v15
	s_movk_i32 s4, 0x3c0
	v_lshlrev_b32_e32 v15, 2, v15
	s_lshl_b32 s93, s1, 6
	s_lshl_b32 s1, s1, 13
	v_and_or_b32 v16, v17, s4, v16
	v_and_b32_e32 v15, 32, v15
	v_bitop3_b32 v17, v16, s1, v15 bitop3:0xde
	s_lshl_b32 s1, s3, 5
	s_and_b32 s50, s1, 0x60
	s_add_i32 m0, s67, 0x18000
	v_lshl_add_u64 v[8:9], v[8:9], 0, s[56:57]
	s_lshl_b32 s1, s50, 7
	s_waitcnt vmcnt(2)
	s_barrier
	global_load_lds_dwordx4 v[8:9], off
	v_lshl_add_u64 v[6:7], v[6:7], 0, s[56:57]
	s_add_i32 m0, s67, 0x1a000
	s_add_i32 s91, s67, 0x8000
	s_add_i32 s3, s67, 0xa000
	global_load_lds_dwordx4 v[6:7], off
	v_lshl_add_u64 v[4:5], v[4:5], 0, s[56:57]
	s_mov_b32 m0, s91
	s_add_u32 s4, s70, 0x40080
	global_load_lds_dwordx4 v[4:5], off
	v_lshl_add_u64 v[2:3], v[2:3], 0, s[56:57]
	s_mov_b32 m0, s3
	s_addc_u32 s5, s71, 0
	global_load_lds_dwordx4 v[2:3], off
	s_add_i32 m0, s67, 0x1c000
	v_lshl_add_u64 v[2:3], s[4:5], 0, v[154:155]
	global_load_lds_dwordx4 v[2:3], off
	v_lshl_add_u64 v[2:3], s[4:5], 0, v[156:157]
	s_add_i32 m0, s67, 0x1e000
	v_readlane_b32 s4, v252, 31
	global_load_lds_dwordx4 v[2:3], off
	v_lshlrev_b32_e32 v2, 14, v0
	v_and_b32_e32 v2, 0xffff8000, v2
	v_lshl_add_u32 v2, v10, 11, v2
	v_and_b32_e32 v0, 1, v0
	v_lshl_or_b32 v0, v0, 6, v2
	v_lshl_add_u32 v158, v11, 1, v0
	v_lshlrev_b32_e32 v0, 14, v12
	v_and_b32_e32 v0, 0xffff8000, v0
	s_waitcnt vmcnt(6)
	v_readlane_b32 s5, v252, 32
	v_lshl_add_u32 v0, v13, 11, v0
	v_and_b32_e32 v2, 1, v12
	s_and_b64 s[4:5], s[4:5], exec
	v_lshl_or_b32 v0, v2, 6, v0
	v_bitop3_b32 v164, s1, v16, v15 bitop3:0xf6
	s_mov_b32 s1, s51
	s_cselect_b32 s4, 5, 6
	v_mov_b32_e32 v159, v1
	v_lshl_add_u32 v160, v14, 1, v0
	v_mov_b32_e32 v161, v1
	s_mov_b32 s52, 0
	v_add_u32_e32 v165, 0, v17
	s_barrier
	v_writelane_b32 v252, s4, 42
	s_branch .LBB0_142

; #define PG8_STAGE(bufoff, gbase, voff) do { _Pragma("unroll") for (int _i = 0; _i < 2; ++_i) \
;     __builtin_amdgcn_global_load_lds((const unsigned*)((const char*)(gbase) + (voff)[_i]), (LAS unsigned*)(lds + (bufoff) + ldsw + _i * 8192), 16, 0, 0); } while (0)
; #define PG8_LDA(dst, b, h) do { _Pragma("unroll") for (int m = 0; m < 4; ++m) _Pragma("unroll") for (int k = 0; k < 2; ++k) dst[m][k] = *(const LAS bf16x8*)(lds + PG8_SA(b, h) + aoff + m * 2048 + k * 1024); } while (0)
; #define PG8_LDB(dst, b, h) do { _Pragma("unroll") for (int n = 0; n < 2; ++n) _Pragma("unroll") for (int k = 0; k < 2; ++k) dst[n][k] = *(const LAS bf16x8*)(lds + PG8_SB(b, h) + boff + n * 2048 + k * 1024); } while (0)
; #define PG8_MMA(ai, bj, At, Bt) do { __builtin_amdgcn_s_setprio(1); _Pragma("unroll") for (int m = 0; m < 4; ++m) _Pragma("unroll") for (int n = 0; n < 2; ++n) _Pragma("unroll") for (int k = 0; k < 2; ++k) \
;     acc[ai][bj][m][n] = __builtin_amdgcn_mfma_f32_16x16x32_bf16(Bt[n][k], At[m][k], acc[ai][bj][m][n], 0, 0, 0); __builtin_amdgcn_s_setprio(0); } while (0)
; #define PG8_WAIT_L(n) asm volatile("s_waitcnt lgkmcnt(" #n ")" ::: "memory")
; #define PG8_BAR __builtin_amdgcn_s_barrier()
; #define PG8_SCHED __builtin_amdgcn_sched_barrier(0)
; template <class Epi, bool HOOK>
; __device__ __forceinline__ void gemm_phase(LAS unsigned char* lds, const Gemm g, const StaticOrder& S, const Epi& E, const int hook_t) {
;     ...
;       const bool last = (t == nt - 2);
;       const char* a1 = cA + (size_t)(t + 1) * kstep;
;       const char* a2 = last ? nA : cA + (size_t)(t + 2) * kstep; const char* b2 = last ? nB : cB + (size_t)(t + 2) * kstep;
;       const char* a3 = a2 + kstep; const char* b3 = b2 + kstep;
;       if (HOOK) { if (t == hook_t) E.hook(acc, cur.pm, cur.pn, wr, wc, fr, fq); }
;       PG8_LDB(B0, 0, 0); PG8_SCHED; PG8_LDA(At, 0, 0); PG8_STAGE(PG8_SA(1, 1), a1 + hstepA, voffA);
;       PG8_WAIT_L(8); PG8_BAR; PG8_WAIT_L(0); PG8_MMA(0, 0, At, B0); PG8_BAR; PG8_SCHED;
;       PG8_LDB(B1, 0, 1); PG8_STAGE(PG8_SB(0, 0), b2, voffB);
.LBB0_149:
	s_add_u32 s58, s24, s70
	s_addc_u32 s59, s25, s71
	s_add_u32 s58, s58, 0x100
	s_addc_u32 s59, s59, 0
	s_add_u32 s76, s97, s70
	s_addc_u32 s77, s83, s71
	s_cmpk_eq_i32 s70, 0x700
	s_cselect_b32 s61, s11, s59
	s_cselect_b32 s60, s53, s58
	s_cselect_b32 s59, s7, s77
	s_cselect_b32 s58, s96, s76
	s_add_i32 s76, 0, 0x10000
	v_add_u32_e32 v0, s76, v164
	ds_read_b128 v[134:137], v0
	ds_read_b128 v[138:141], v0 offset:1024
	ds_read_b128 v[142:145], v0 offset:2048
	ds_read_b128 v[146:149], v0 offset:3072
	v_lshl_add_u64 v[162:163], v[130:131], 0, s[70:71]
	s_add_i32 m0, s67, 0xc000
	ds_read_b128 v[150:153], v165
	ds_read_b128 v[166:169], v165 offset:1024
	ds_read_b128 v[190:193], v165 offset:2048
	ds_read_b128 v[194:197], v165 offset:3072
	ds_read_b128 v[198:201], v165 offset:4096
	ds_read_b128 v[202:205], v165 offset:5120
	ds_read_b128 v[206:209], v165 offset:6144
	ds_read_b128 v[210:213], v165 offset:7168
	global_load_lds_dwordx4 v[162:163], off
	v_lshl_add_u64 v[162:163], v[132:133], 0, s[70:71]
	s_add_i32 m0, s67, 0xe000
	s_nop 0
	global_load_lds_dwordx4 v[162:163], off
	s_add_i32 s95, 0, 0x14000
	s_add_i32 s76, s76, s9
	v_add_u32_e32 v0, s95, v164
	ds_read_b128 v[214:217], v0
	ds_read_b128 v[218:221], v0 offset:1024
	ds_read_b128 v[222:225], v0 offset:2048
	ds_read_b128 v[226:229], v0 offset:3072
	s_cmp_eq_u32 s86, -2
	s_cbranch_scc0 .Lmrg_a0_strict
	s_cmp_gt_u32 s52, 1
	s_cbranch_scc1 .Lmrg_a0_relaxed

; #define PG8_STAGE(bufoff, gbase, voff) do { _Pragma("unroll") for (int _i = 0; _i < 2; ++_i) \
;     __builtin_amdgcn_global_load_lds((const unsigned*)((const char*)(gbase) + (voff)[_i]), (LAS unsigned*)(lds + (bufoff) + ldsw + _i * 8192), 16, 0, 0); } while (0)
; #define PG8_LDA(dst, b, h) do { _Pragma("unroll") for (int m = 0; m < 4; ++m) _Pragma("unroll") for (int k = 0; k < 2; ++k) dst[m][k] = *(const LAS bf16x8*)(lds + PG8_SA(b, h) + aoff + m * 2048 + k * 1024); } while (0)
; #define PG8_LDB(dst, b, h) do { _Pragma("unroll") for (int n = 0; n < 2; ++n) _Pragma("unroll") for (int k = 0; k < 2; ++k) dst[n][k] = *(const LAS bf16x8*)(lds + PG8_SB(b, h) + boff + n * 2048 + k * 1024); } while (0)
; #define PG8_MMA(ai, bj, At, Bt) do { __builtin_amdgcn_s_setprio(1); _Pragma("unroll") for (int m = 0; m < 4; ++m) _Pragma("unroll") for (int n = 0; n < 2; ++n) _Pragma("unroll") for (int k = 0; k < 2; ++k) \
;     acc[ai][bj][m][n] = __builtin_amdgcn_mfma_f32_16x16x32_bf16(Bt[n][k], At[m][k], acc[ai][bj][m][n], 0, 0, 0); __builtin_amdgcn_s_setprio(0); } while (0)
; #define PG8_WAIT_L(n) asm volatile("s_waitcnt lgkmcnt(" #n ")" ::: "memory")
; #define PG8_BAR __builtin_amdgcn_s_barrier()
; #define PG8_SCHED __builtin_amdgcn_sched_barrier(0)
; template <class Epi, bool HOOK>
; __device__ __forceinline__ void gemm_phase(LAS unsigned char* lds, const Gemm g, const StaticOrder& S, const Epi& E, const int hook_t) {
;     ...
;       PG8_WAIT_L(8); PG8_BAR; PG8_WAIT_L(0); PG8_MMA(0, 0, At, B0); PG8_BAR; PG8_SCHED;
;       PG8_LDB(B1, 0, 1); PG8_STAGE(PG8_SB(0, 0), b2, voffB);
;       PG8_BAR; PG8_WAIT_L(0); PG8_MMA(0, 1, At, B1); PG8_BAR;
;       PG8_LDA(At, 0, 1); PG8_STAGE(PG8_SA(0, 0), a2, voffA);
;       PG8_BAR; PG8_WAIT_L(0); PG8_MMA(1, 0, At, B0); PG8_BAR; PG8_SCHED;
;       PG8_STAGE(PG8_SB(0, 1), b2 + hstepB, voffB);
.Lmrg_a0_go:
	s_barrier
	s_setprio 1
	v_mfma_f32_16x16x32_bf16 v[126:129], v[134:137], v[150:153], v[126:129]
	v_mfma_f32_16x16x32_bf16 v[122:125], v[142:145], v[150:153], v[122:125]
	v_mfma_f32_16x16x32_bf16 v[118:121], v[134:137], v[190:193], v[118:121]
	v_mfma_f32_16x16x32_bf16 v[114:117], v[142:145], v[190:193], v[114:117]
	v_mfma_f32_16x16x32_bf16 v[94:97], v[134:137], v[198:201], v[94:97]
	v_mfma_f32_16x16x32_bf16 v[90:93], v[142:145], v[198:201], v[90:93]
	v_mfma_f32_16x16x32_bf16 v[78:81], v[134:137], v[206:209], v[78:81]
	v_mfma_f32_16x16x32_bf16 v[74:77], v[142:145], v[206:209], v[74:77]
	v_mfma_f32_16x16x32_bf16 v[126:129], v[138:141], v[166:169], v[126:129]
	v_mfma_f32_16x16x32_bf16 v[122:125], v[146:149], v[166:169], v[122:125]
	v_mfma_f32_16x16x32_bf16 v[118:121], v[138:141], v[194:197], v[118:121]
	v_mfma_f32_16x16x32_bf16 v[114:117], v[146:149], v[194:197], v[114:117]
	v_mfma_f32_16x16x32_bf16 v[94:97], v[138:141], v[202:205], v[94:97]
	v_mfma_f32_16x16x32_bf16 v[90:93], v[146:149], v[202:205], v[90:93]
	v_mfma_f32_16x16x32_bf16 v[78:81], v[138:141], v[210:213], v[78:81]
	v_mfma_f32_16x16x32_bf16 v[74:77], v[146:149], v[210:213], v[74:77]
	v_mfma_f32_16x16x32_bf16 v[110:113], v[214:217], v[150:153], v[110:113]
	v_mfma_f32_16x16x32_bf16 v[106:109], v[222:225], v[150:153], v[106:109]
	v_mfma_f32_16x16x32_bf16 v[102:105], v[214:217], v[190:193], v[102:105]
	v_mfma_f32_16x16x32_bf16 v[98:101], v[222:225], v[190:193], v[98:101]
	v_mfma_f32_16x16x32_bf16 v[86:89], v[214:217], v[198:201], v[86:89]
	v_mfma_f32_16x16x32_bf16 v[82:85], v[222:225], v[198:201], v[82:85]
	v_mfma_f32_16x16x32_bf16 v[70:73], v[214:217], v[206:209], v[70:73]
	v_mfma_f32_16x16x32_bf16 v[66:69], v[222:225], v[206:209], v[66:69]
	v_mfma_f32_16x16x32_bf16 v[110:113], v[218:221], v[166:169], v[110:113]
	v_mfma_f32_16x16x32_bf16 v[106:109], v[226:229], v[166:169], v[106:109]
	v_mfma_f32_16x16x32_bf16 v[102:105], v[218:221], v[194:197], v[102:105]
	v_mfma_f32_16x16x32_bf16 v[98:101], v[226:229], v[194:197], v[98:101]
	v_mfma_f32_16x16x32_bf16 v[86:89], v[218:221], v[202:205], v[86:89]
	v_mfma_f32_16x16x32_bf16 v[82:85], v[226:229], v[202:205], v[82:85]
	v_mfma_f32_16x16x32_bf16 v[70:73], v[218:221], v[210:213], v[70:73]
	v_mfma_f32_16x16x32_bf16 v[66:69], v[226:229], v[210:213], v[66:69]
	s_setprio 0
	s_barrier
	ds_read_b128 v[150:153], v165 offset:16384
	ds_read_b128 v[166:169], v165 offset:17408
	ds_read_b128 v[190:193], v165 offset:18432
	ds_read_b128 v[194:197], v165 offset:19456
	ds_read_b128 v[198:201], v165 offset:20480
	ds_read_b128 v[202:205], v165 offset:21504
	ds_read_b128 v[206:209], v165 offset:22528
	ds_read_b128 v[210:213], v165 offset:23552
	v_lshl_add_u64 v[162:163], s[58:59], 0, v[154:155]
	s_mov_b32 m0, s76
	v_lshl_add_u64 v[230:231], s[58:59], 0, v[156:157]
	global_load_lds_dwordx4 v[162:163], off
	s_add_i32 m0, s76, 0x2000
	s_nop 0
	global_load_lds_dwordx4 v[230:231], off
	s_mov_b32 m0, s67
	v_lshl_add_u64 v[232:233], s[60:61], 0, v[154:155]
	global_load_lds_dwordx4 v[232:233], off
	v_lshl_add_u64 v[234:235], s[60:61], 0, v[156:157]
	s_mov_b32 m0, s65
	s_nop 0
	global_load_lds_dwordx4 v[234:235], off
	s_add_u32 s76, s58, 0x40000
	s_addc_u32 s77, s59, 0
	s_add_i32 s95, s95, s9
	v_lshl_add_u64 v[162:163], s[76:77], 0, v[154:155]
	s_mov_b32 m0, s95
	s_nop 0
	global_load_lds_dwordx4 v[162:163], off
	v_lshl_add_u64 v[162:163], s[76:77], 0, v[156:157]
	s_add_i32 m0, s95, 0x2000
	s_nop 0
	global_load_lds_dwordx4 v[162:163], off
	s_cmp_eq_u32 s86, -2
	s_cbranch_scc0 .Lmrg_b0_strict
	s_cmp_gt_u32 s52, 1
	s_cbranch_scc1 .Lmrg_b0_relaxed

; #define PG8_STAGE(bufoff, gbase, voff) do { _Pragma("unroll") for (int _i = 0; _i < 2; ++_i) \
;     __builtin_amdgcn_global_load_lds((const unsigned*)((const char*)(gbase) + (voff)[_i]), (LAS unsigned*)(lds + (bufoff) + ldsw + _i * 8192), 16, 0, 0); } while (0)
; #define PG8_LDA(dst, b, h) do { _Pragma("unroll") for (int m = 0; m < 4; ++m) _Pragma("unroll") for (int k = 0; k < 2; ++k) dst[m][k] = *(const LAS bf16x8*)(lds + PG8_SA(b, h) + aoff + m * 2048 + k * 1024); } while (0)
; #define PG8_LDB(dst, b, h) do { _Pragma("unroll") for (int n = 0; n < 2; ++n) _Pragma("unroll") for (int k = 0; k < 2; ++k) dst[n][k] = *(const LAS bf16x8*)(lds + PG8_SB(b, h) + boff + n * 2048 + k * 1024); } while (0)
; #define PG8_MMA(ai, bj, At, Bt) do { __builtin_amdgcn_s_setprio(1); _Pragma("unroll") for (int m = 0; m < 4; ++m) _Pragma("unroll") for (int n = 0; n < 2; ++n) _Pragma("unroll") for (int k = 0; k < 2; ++k) \
;     acc[ai][bj][m][n] = __builtin_amdgcn_mfma_f32_16x16x32_bf16(Bt[n][k], At[m][k], acc[ai][bj][m][n], 0, 0, 0); __builtin_amdgcn_s_setprio(0); } while (0)
; #define PG8_WAIT_V(n) asm volatile("s_waitcnt vmcnt(" #n ")" ::: "memory")
; #define PG8_WAIT_L(n) asm volatile("s_waitcnt lgkmcnt(" #n ")" ::: "memory")
; #define PG8_BAR __builtin_amdgcn_s_barrier()
; #define PG8_SCHED __builtin_amdgcn_sched_barrier(0)
; template <class Epi, bool HOOK>
; __device__ __forceinline__ void gemm_phase(LAS unsigned char* lds, const Gemm g, const StaticOrder& S, const Epi& E, const int hook_t) {
;     ...
;       PG8_BAR; PG8_WAIT_L(0); PG8_MMA(1, 0, At, B0); PG8_BAR; PG8_SCHED;
;       PG8_STAGE(PG8_SB(0, 1), b2 + hstepB, voffB);
;       PG8_WAIT_V(6); PG8_BAR; PG8_MMA(1, 1, At, B1); PG8_BAR;
;       PG8_LDB(B0, 1, 0); PG8_SCHED; PG8_LDA(At, 1, 0); PG8_STAGE(PG8_SA(0, 1), a2 + hstepA, voffA);
;       PG8_WAIT_L(8); PG8_BAR; PG8_WAIT_L(0); PG8_MMA(0, 0, At, B0); PG8_BAR; PG8_SCHED;
;       PG8_LDB(B1, 1, 1); PG8_STAGE(PG8_SB(1, 0), b3, voffB);
;       PG8_BAR; PG8_WAIT_L(0); PG8_MMA(0, 1, At, B1); PG8_BAR;
.Lmrg_b0_go:
	s_barrier
	s_setprio 1
	v_mfma_f32_16x16x32_bf16 v[62:65], v[134:137], v[150:153], v[62:65]
	v_mfma_f32_16x16x32_bf16 v[58:61], v[142:145], v[150:153], v[58:61]
	v_mfma_f32_16x16x32_bf16 v[46:49], v[134:137], v[190:193], v[46:49]
	v_mfma_f32_16x16x32_bf16 v[42:45], v[142:145], v[190:193], v[42:45]
	v_mfma_f32_16x16x32_bf16 v[38:41], v[134:137], v[198:201], v[38:41]
	v_mfma_f32_16x16x32_bf16 v[30:33], v[142:145], v[198:201], v[30:33]
	v_mfma_f32_16x16x32_bf16 v[22:25], v[134:137], v[206:209], v[22:25]
	v_mfma_f32_16x16x32_bf16 v[14:17], v[142:145], v[206:209], v[14:17]
	v_mfma_f32_16x16x32_bf16 v[62:65], v[138:141], v[166:169], v[62:65]
	v_mfma_f32_16x16x32_bf16 v[58:61], v[146:149], v[166:169], v[58:61]
	v_mfma_f32_16x16x32_bf16 v[46:49], v[138:141], v[194:197], v[46:49]
	v_mfma_f32_16x16x32_bf16 v[42:45], v[146:149], v[194:197], v[42:45]
	v_mfma_f32_16x16x32_bf16 v[38:41], v[138:141], v[202:205], v[38:41]
	v_mfma_f32_16x16x32_bf16 v[30:33], v[146:149], v[202:205], v[30:33]
	v_mfma_f32_16x16x32_bf16 v[22:25], v[138:141], v[210:213], v[22:25]
	v_mfma_f32_16x16x32_bf16 v[14:17], v[146:149], v[210:213], v[14:17]
	v_mfma_f32_16x16x32_bf16 v[54:57], v[214:217], v[150:153], v[54:57]
	v_mfma_f32_16x16x32_bf16 v[50:53], v[222:225], v[150:153], v[50:53]
	v_mfma_f32_16x16x32_bf16 v[34:37], v[214:217], v[190:193], v[34:37]
	v_mfma_f32_16x16x32_bf16 v[26:29], v[222:225], v[190:193], v[26:29]
	v_mfma_f32_16x16x32_bf16 v[18:21], v[214:217], v[198:201], v[18:21]
	v_mfma_f32_16x16x32_bf16 v[10:13], v[222:225], v[198:201], v[10:13]
	v_mfma_f32_16x16x32_bf16 v[6:9], v[214:217], v[206:209], v[6:9]
	v_mfma_f32_16x16x32_bf16 v[2:5], v[222:225], v[206:209], v[2:5]
	v_mfma_f32_16x16x32_bf16 v[54:57], v[218:221], v[166:169], v[54:57]
	v_mfma_f32_16x16x32_bf16 v[50:53], v[226:229], v[166:169], v[50:53]
	v_mfma_f32_16x16x32_bf16 v[34:37], v[218:221], v[194:197], v[34:37]
	v_mfma_f32_16x16x32_bf16 v[26:29], v[226:229], v[194:197], v[26:29]
	v_mfma_f32_16x16x32_bf16 v[18:21], v[218:221], v[202:205], v[18:21]
	v_mfma_f32_16x16x32_bf16 v[10:13], v[226:229], v[202:205], v[10:13]
	v_mfma_f32_16x16x32_bf16 v[6:9], v[218:221], v[210:213], v[6:9]
	v_mfma_f32_16x16x32_bf16 v[2:5], v[226:229], v[210:213], v[2:5]
	s_setprio 0
	s_add_i32 s76, 0, 0x18000
	v_add_u32_e32 v0, s76, v164
	s_barrier
	ds_read_b128 v[134:137], v0
	ds_read_b128 v[138:141], v0 offset:1024
	ds_read_b128 v[142:145], v0 offset:2048
	ds_read_b128 v[146:149], v0 offset:3072
	s_add_u32 s60, s60, 0x40000
	s_addc_u32 s61, s61, 0
	s_mov_b32 m0, s80
	v_lshl_add_u64 v[214:215], s[60:61], 0, v[154:155]
	ds_read_b128 v[150:153], v165 offset:32768
	ds_read_b128 v[166:169], v165 offset:33792
	ds_read_b128 v[190:193], v165 offset:34816
	ds_read_b128 v[194:197], v165 offset:35840
	ds_read_b128 v[198:201], v165 offset:36864
	ds_read_b128 v[202:205], v165 offset:37888
	ds_read_b128 v[206:209], v165 offset:38912
	ds_read_b128 v[210:213], v165 offset:39936
	global_load_lds_dwordx4 v[214:215], off
	v_lshl_add_u64 v[214:215], s[60:61], 0, v[156:157]
	s_mov_b32 m0, s92
	s_nop 0
	global_load_lds_dwordx4 v[214:215], off
	s_add_i32 s60, 0, 0x1c000
	s_add_i32 s61, s76, s9
	v_add_u32_e32 v0, s60, v164
	ds_read_b128 v[214:217], v0
	ds_read_b128 v[218:221], v0 offset:1024
	ds_read_b128 v[222:225], v0 offset:2048
	ds_read_b128 v[226:229], v0 offset:3072
	s_waitcnt vmcnt(8) lgkmcnt(0)
	s_barrier
	s_setprio 1
	v_mfma_f32_16x16x32_bf16 v[126:129], v[134:137], v[150:153], v[126:129]
	v_mfma_f32_16x16x32_bf16 v[122:125], v[142:145], v[150:153], v[122:125]
	v_mfma_f32_16x16x32_bf16 v[118:121], v[134:137], v[190:193], v[118:121]
	v_mfma_f32_16x16x32_bf16 v[114:117], v[142:145], v[190:193], v[114:117]
	v_mfma_f32_16x16x32_bf16 v[94:97], v[134:137], v[198:201], v[94:97]
	v_mfma_f32_16x16x32_bf16 v[90:93], v[142:145], v[198:201], v[90:93]
	v_mfma_f32_16x16x32_bf16 v[78:81], v[134:137], v[206:209], v[78:81]
	v_mfma_f32_16x16x32_bf16 v[74:77], v[142:145], v[206:209], v[74:77]
	v_mfma_f32_16x16x32_bf16 v[126:129], v[138:141], v[166:169], v[126:129]
	v_mfma_f32_16x16x32_bf16 v[122:125], v[146:149], v[166:169], v[122:125]
	v_mfma_f32_16x16x32_bf16 v[118:121], v[138:141], v[194:197], v[118:121]
	v_mfma_f32_16x16x32_bf16 v[114:117], v[146:149], v[194:197], v[114:117]
	v_mfma_f32_16x16x32_bf16 v[94:97], v[138:141], v[202:205], v[94:97]
	v_mfma_f32_16x16x32_bf16 v[90:93], v[146:149], v[202:205], v[90:93]
	v_mfma_f32_16x16x32_bf16 v[78:81], v[138:141], v[210:213], v[78:81]
	v_mfma_f32_16x16x32_bf16 v[74:77], v[146:149], v[210:213], v[74:77]
	v_mfma_f32_16x16x32_bf16 v[110:113], v[214:217], v[150:153], v[110:113]
	v_mfma_f32_16x16x32_bf16 v[106:109], v[222:225], v[150:153], v[106:109]
	v_mfma_f32_16x16x32_bf16 v[102:105], v[214:217], v[190:193], v[102:105]
	v_mfma_f32_16x16x32_bf16 v[98:101], v[222:225], v[190:193], v[98:101]
	v_mfma_f32_16x16x32_bf16 v[86:89], v[214:217], v[198:201], v[86:89]
	v_mfma_f32_16x16x32_bf16 v[82:85], v[222:225], v[198:201], v[82:85]
	v_mfma_f32_16x16x32_bf16 v[70:73], v[214:217], v[206:209], v[70:73]
	v_mfma_f32_16x16x32_bf16 v[66:69], v[222:225], v[206:209], v[66:69]
	v_mfma_f32_16x16x32_bf16 v[110:113], v[218:221], v[166:169], v[110:113]
	v_mfma_f32_16x16x32_bf16 v[106:109], v[226:229], v[166:169], v[106:109]
	v_mfma_f32_16x16x32_bf16 v[102:105], v[218:221], v[194:197], v[102:105]
	v_mfma_f32_16x16x32_bf16 v[98:101], v[226:229], v[194:197], v[98:101]
	v_mfma_f32_16x16x32_bf16 v[86:89], v[218:221], v[202:205], v[86:89]
	v_mfma_f32_16x16x32_bf16 v[82:85], v[226:229], v[202:205], v[82:85]
	v_mfma_f32_16x16x32_bf16 v[70:73], v[218:221], v[210:213], v[70:73]
	v_mfma_f32_16x16x32_bf16 v[66:69], v[226:229], v[210:213], v[66:69]
	s_setprio 0
	s_barrier
; #define PG8_STAGE(bufoff, gbase, voff) do { _Pragma("unroll") for (int _i = 0; _i < 2; ++_i) \
;     __builtin_amdgcn_global_load_lds((const unsigned*)((const char*)(gbase) + (voff)[_i]), (LAS unsigned*)(lds + (bufoff) + ldsw + _i * 8192), 16, 0, 0); } while (0)
; #define PG8_LDA(dst, b, h) do { _Pragma("unroll") for (int m = 0; m < 4; ++m) _Pragma("unroll") for (int k = 0; k < 2; ++k) dst[m][k] = *(const LAS bf16x8*)(lds + PG8_SA(b, h) + aoff + m * 2048 + k * 1024); } while (0)
; #define PG8_MMA(ai, bj, At, Bt) do { __builtin_amdgcn_s_setprio(1); _Pragma("unroll") for (int m = 0; m < 4; ++m) _Pragma("unroll") for (int n = 0; n < 2; ++n) _Pragma("unroll") for (int k = 0; k < 2; ++k) \
;     acc[ai][bj][m][n] = __builtin_amdgcn_mfma_f32_16x16x32_bf16(Bt[n][k], At[m][k], acc[ai][bj][m][n], 0, 0, 0); __builtin_amdgcn_s_setprio(0); } while (0)
; #define PG8_WAIT_V(n) asm volatile("s_waitcnt vmcnt(" #n ")" ::: "memory")
; #define PG8_WAIT_L(n) asm volatile("s_waitcnt lgkmcnt(" #n ")" ::: "memory")
; #define PG8_BAR __builtin_amdgcn_s_barrier()
; #define PG8_SCHED __builtin_amdgcn_sched_barrier(0)
; template <class Epi, bool HOOK>
; __device__ __forceinline__ void gemm_phase(LAS unsigned char* lds, const Gemm g, const StaticOrder& S, const Epi& E, const int hook_t) {
;     ...
;       PG8_LDA(At, 1, 1); PG8_STAGE(PG8_SA(1, 0), a3, voffA);
;       PG8_BAR; PG8_WAIT_L(0); PG8_MMA(1, 0, At, B0); PG8_BAR; PG8_SCHED;
;       PG8_STAGE(PG8_SB(1, 1), b3 + hstepB, voffB);
;       PG8_WAIT_V(6); PG8_BAR; PG8_MMA(1, 1, At, B1); PG8_BAR;
;     }
	ds_read_b128 v[150:153], v165 offset:49152
	ds_read_b128 v[166:169], v165 offset:50176
	ds_read_b128 v[190:193], v165 offset:51200
	ds_read_b128 v[194:197], v165 offset:52224
	ds_read_b128 v[198:201], v165 offset:53248
	ds_read_b128 v[202:205], v165 offset:54272
	ds_read_b128 v[206:209], v165 offset:55296
	ds_read_b128 v[210:213], v165 offset:56320
	s_mov_b32 m0, s61
	v_lshl_add_u64 v[162:163], s[58:59], 0, v[154:155]
	v_lshl_add_u64 v[162:163], v[162:163], 0, s[56:57]
	global_load_lds_dwordx4 v[162:163], off
	v_lshl_add_u64 v[162:163], v[230:231], 0, s[56:57]
	s_add_i32 m0, s61, 0x2000
	s_nop 0
	global_load_lds_dwordx4 v[162:163], off
	s_mov_b32 m0, s91
	v_lshl_add_u64 v[162:163], v[232:233], 0, s[56:57]
	global_load_lds_dwordx4 v[162:163], off
	v_lshl_add_u64 v[162:163], v[234:235], 0, s[56:57]
	s_mov_b32 m0, s3
	s_nop 0
	global_load_lds_dwordx4 v[162:163], off
	s_add_u32 s58, s58, 0x40080
	s_addc_u32 s59, s59, 0
	s_add_i32 s60, s60, s9
	v_lshl_add_u64 v[162:163], s[58:59], 0, v[154:155]
	s_mov_b32 m0, s60
	s_nop 0
	global_load_lds_dwordx4 v[162:163], off
	v_lshl_add_u64 v[162:163], s[58:59], 0, v[156:157]
	s_add_i32 m0, s60, 0x2000
	s_nop 0
	global_load_lds_dwordx4 v[162:163], off
	s_waitcnt vmcnt(8) lgkmcnt(0)
	s_barrier
	s_setprio 1
	v_mfma_f32_16x16x32_bf16 v[62:65], v[134:137], v[150:153], v[62:65]
	v_mfma_f32_16x16x32_bf16 v[58:61], v[142:145], v[150:153], v[58:61]
	v_mfma_f32_16x16x32_bf16 v[46:49], v[134:137], v[190:193], v[46:49]
	v_mfma_f32_16x16x32_bf16 v[42:45], v[142:145], v[190:193], v[42:45]
	v_mfma_f32_16x16x32_bf16 v[38:41], v[134:137], v[198:201], v[38:41]
	v_mfma_f32_16x16x32_bf16 v[30:33], v[142:145], v[198:201], v[30:33]
	v_mfma_f32_16x16x32_bf16 v[22:25], v[134:137], v[206:209], v[22:25]
	v_mfma_f32_16x16x32_bf16 v[14:17], v[142:145], v[206:209], v[14:17]
	v_mfma_f32_16x16x32_bf16 v[62:65], v[138:141], v[166:169], v[62:65]
	v_mfma_f32_16x16x32_bf16 v[58:61], v[146:149], v[166:169], v[58:61]
	v_mfma_f32_16x16x32_bf16 v[46:49], v[138:141], v[194:197], v[46:49]
	v_mfma_f32_16x16x32_bf16 v[42:45], v[146:149], v[194:197], v[42:45]
	v_mfma_f32_16x16x32_bf16 v[38:41], v[138:141], v[202:205], v[38:41]
	v_mfma_f32_16x16x32_bf16 v[30:33], v[146:149], v[202:205], v[30:33]
	v_mfma_f32_16x16x32_bf16 v[22:25], v[138:141], v[210:213], v[22:25]
	v_mfma_f32_16x16x32_bf16 v[14:17], v[146:149], v[210:213], v[14:17]
	v_mfma_f32_16x16x32_bf16 v[54:57], v[214:217], v[150:153], v[54:57]
	v_mfma_f32_16x16x32_bf16 v[50:53], v[222:225], v[150:153], v[50:53]
	v_mfma_f32_16x16x32_bf16 v[34:37], v[214:217], v[190:193], v[34:37]
	v_mfma_f32_16x16x32_bf16 v[26:29], v[222:225], v[190:193], v[26:29]
	v_mfma_f32_16x16x32_bf16 v[18:21], v[214:217], v[198:201], v[18:21]
	v_mfma_f32_16x16x32_bf16 v[10:13], v[222:225], v[198:201], v[10:13]
	v_mfma_f32_16x16x32_bf16 v[6:9], v[214:217], v[206:209], v[6:9]
	v_mfma_f32_16x16x32_bf16 v[2:5], v[222:225], v[206:209], v[2:5]
	v_mfma_f32_16x16x32_bf16 v[54:57], v[218:221], v[166:169], v[54:57]
	v_mfma_f32_16x16x32_bf16 v[50:53], v[226:229], v[166:169], v[50:53]
	v_mfma_f32_16x16x32_bf16 v[34:37], v[218:221], v[194:197], v[34:37]
	v_mfma_f32_16x16x32_bf16 v[26:29], v[226:229], v[194:197], v[26:29]
	v_mfma_f32_16x16x32_bf16 v[18:21], v[218:221], v[202:205], v[18:21]
	v_mfma_f32_16x16x32_bf16 v[10:13], v[226:229], v[202:205], v[10:13]
	v_mfma_f32_16x16x32_bf16 v[6:9], v[218:221], v[210:213], v[6:9]
	v_mfma_f32_16x16x32_bf16 v[2:5], v[226:229], v[210:213], v[2:5]
	s_setprio 0
	s_add_i32 s86, s86, 2
	s_add_u32 s70, s70, 0x100
	s_addc_u32 s71, s71, 0
	s_cmp_gt_u32 s86, 13
	s_barrier
	s_cbranch_scc1 .LBB0_141

; #define PG8_STAGE(bufoff, gbase, voff) do { _Pragma("unroll") for (int _i = 0; _i < 2; ++_i) \
;     __builtin_amdgcn_global_load_lds((const unsigned*)((const char*)(gbase) + (voff)[_i]), (LAS unsigned*)(lds + (bufoff) + ldsw + _i * 8192), 16, 0, 0); } while (0)
; #define PG8_LDA(dst, b, h) do { _Pragma("unroll") for (int m = 0; m < 4; ++m) _Pragma("unroll") for (int k = 0; k < 2; ++k) dst[m][k] = *(const LAS bf16x8*)(lds + PG8_SA(b, h) + aoff + m * 2048 + k * 1024); } while (0)
; #define PG8_LDB(dst, b, h) do { _Pragma("unroll") for (int n = 0; n < 2; ++n) _Pragma("unroll") for (int k = 0; k < 2; ++k) dst[n][k] = *(const LAS bf16x8*)(lds + PG8_SB(b, h) + boff + n * 2048 + k * 1024); } while (0)
; #define PG8_MMA(ai, bj, At, Bt) do { __builtin_amdgcn_s_setprio(1); _Pragma("unroll") for (int m = 0; m < 4; ++m) _Pragma("unroll") for (int n = 0; n < 2; ++n) _Pragma("unroll") for (int k = 0; k < 2; ++k) \
;     acc[ai][bj][m][n] = __builtin_amdgcn_mfma_f32_16x16x32_bf16(Bt[n][k], At[m][k], acc[ai][bj][m][n], 0, 0, 0); __builtin_amdgcn_s_setprio(0); } while (0)
; #define PG8_WAIT_L(n) asm volatile("s_waitcnt lgkmcnt(" #n ")" ::: "memory")
; #define PG8_BAR __builtin_amdgcn_s_barrier()
; #define PG8_SCHED __builtin_amdgcn_sched_barrier(0)
; template <class Epi, bool HOOK>
; __device__ __forceinline__ void gemm_phase(LAS unsigned char* lds, const Gemm g, const StaticOrder& S, const Epi& E, const int hook_t) {
;     ...
;       const bool last = (t == nt - 2);
;       const char* a1 = cA + (size_t)(t + 1) * kstep;
;       const char* a2 = last ? nA : cA + (size_t)(t + 2) * kstep; const char* b2 = last ? nB : cB + (size_t)(t + 2) * kstep;
;       const char* a3 = a2 + kstep; const char* b3 = b2 + kstep;
;       if (HOOK) { if (t == hook_t) E.hook(acc, cur.pm, cur.pn, wr, wc, fr, fq); }
;       PG8_LDB(B0, 0, 0); PG8_SCHED; PG8_LDA(At, 0, 0); PG8_STAGE(PG8_SA(1, 1), a1 + hstepA, voffA);
;       PG8_WAIT_L(8); PG8_BAR; PG8_WAIT_L(0); PG8_MMA(0, 0, At, B0); PG8_BAR; PG8_SCHED;
;       PG8_LDB(B1, 0, 1); PG8_STAGE(PG8_SB(0, 0), b2, voffB);
.LBB0_216:
	s_add_u32 s20, s6, 0xfffc0080
	s_addc_u32 s21, s7, -1
	s_add_i32 s43, 0, 0x10000
	v_add_u32_e32 v0, s43, v191
	ds_read_b128 v[130:133], v0
	ds_read_b128 v[134:137], v0 offset:1024
	ds_read_b128 v[152:155], v0 offset:2048
	ds_read_b128 v[156:159], v0 offset:3072
	s_cmp_eq_u32 s42, 12
	s_cselect_b32 s23, s1, s21
	s_cselect_b32 s22, s3, s20
	s_cselect_b32 s21, s11, s41
	s_cselect_b32 s20, s13, s40
	v_lshl_add_u64 v[168:169], s[6:7], 0, v[146:147]
	s_add_i32 m0, s19, 0xc000
	ds_read_b128 v[160:163], v193
	ds_read_b128 v[164:167], v193 offset:1024
	ds_read_b128 v[194:197], v193 offset:2048
	ds_read_b128 v[198:201], v193 offset:3072
	ds_read_b128 v[202:205], v193 offset:4096
	ds_read_b128 v[206:209], v193 offset:5120
	ds_read_b128 v[210:213], v193 offset:6144
	ds_read_b128 v[214:217], v193 offset:7168
	global_load_lds_dwordx4 v[168:169], off
	v_lshl_add_u64 v[168:169], s[6:7], 0, v[148:149]
	s_add_i32 m0, s19, 0xe000
	s_nop 0
	global_load_lds_dwordx4 v[168:169], off
	s_add_i32 s46, 0, 0x14000
	v_add_u32_e32 v0, s46, v191
	s_add_i32 s43, s43, s26
	ds_read_b128 v[218:221], v0
	ds_read_b128 v[222:225], v0 offset:1024
	ds_read_b128 v[226:229], v0 offset:2048
	ds_read_b128 v[230:233], v0 offset:3072
	s_cmp_eq_u32 s42, -2
	s_cbranch_scc0 .Lwin_a0_strict
	s_cmp_gt_u32 s38, 1
	s_cbranch_scc1 .Lwin_a0_relaxed

; #define PG8_STAGE(bufoff, gbase, voff) do { _Pragma("unroll") for (int _i = 0; _i < 2; ++_i) \
;     __builtin_amdgcn_global_load_lds((const unsigned*)((const char*)(gbase) + (voff)[_i]), (LAS unsigned*)(lds + (bufoff) + ldsw + _i * 8192), 16, 0, 0); } while (0)
; #define PG8_LDA(dst, b, h) do { _Pragma("unroll") for (int m = 0; m < 4; ++m) _Pragma("unroll") for (int k = 0; k < 2; ++k) dst[m][k] = *(const LAS bf16x8*)(lds + PG8_SA(b, h) + aoff + m * 2048 + k * 1024); } while (0)
; #define PG8_LDB(dst, b, h) do { _Pragma("unroll") for (int n = 0; n < 2; ++n) _Pragma("unroll") for (int k = 0; k < 2; ++k) dst[n][k] = *(const LAS bf16x8*)(lds + PG8_SB(b, h) + boff + n * 2048 + k * 1024); } while (0)
; #define PG8_MMA(ai, bj, At, Bt) do { __builtin_amdgcn_s_setprio(1); _Pragma("unroll") for (int m = 0; m < 4; ++m) _Pragma("unroll") for (int n = 0; n < 2; ++n) _Pragma("unroll") for (int k = 0; k < 2; ++k) \
;     acc[ai][bj][m][n] = __builtin_amdgcn_mfma_f32_16x16x32_bf16(Bt[n][k], At[m][k], acc[ai][bj][m][n], 0, 0, 0); __builtin_amdgcn_s_setprio(0); } while (0)
; #define PG8_WAIT_L(n) asm volatile("s_waitcnt lgkmcnt(" #n ")" ::: "memory")
; #define PG8_BAR __builtin_amdgcn_s_barrier()
; #define PG8_SCHED __builtin_amdgcn_sched_barrier(0)
; template <class Epi, bool HOOK>
; __device__ __forceinline__ void gemm_phase(LAS unsigned char* lds, const Gemm g, const StaticOrder& S, const Epi& E, const int hook_t) {
;     ...
;       PG8_WAIT_L(8); PG8_BAR; PG8_WAIT_L(0); PG8_MMA(0, 0, At, B0); PG8_BAR; PG8_SCHED;
;       PG8_LDB(B1, 0, 1); PG8_STAGE(PG8_SB(0, 0), b2, voffB);
;       PG8_BAR; PG8_WAIT_L(0); PG8_MMA(0, 1, At, B1); PG8_BAR;
;       PG8_LDA(At, 0, 1); PG8_STAGE(PG8_SA(0, 0), a2, voffA);
;       PG8_BAR; PG8_WAIT_L(0); PG8_MMA(1, 0, At, B0); PG8_BAR; PG8_SCHED;
;       PG8_STAGE(PG8_SB(0, 1), b2 + hstepB, voffB);
.Lwin_a0_go:
	s_barrier
	s_setprio 1
	v_mfma_f32_16x16x32_bf16 v[126:129], v[130:133], v[160:163], v[126:129]
	v_mfma_f32_16x16x32_bf16 v[122:125], v[152:155], v[160:163], v[122:125]
	v_mfma_f32_16x16x32_bf16 v[110:113], v[130:133], v[194:197], v[110:113]
	v_mfma_f32_16x16x32_bf16 v[106:109], v[152:155], v[194:197], v[106:109]
	v_mfma_f32_16x16x32_bf16 v[94:97], v[130:133], v[202:205], v[94:97]
	v_mfma_f32_16x16x32_bf16 v[90:93], v[152:155], v[202:205], v[90:93]
	v_mfma_f32_16x16x32_bf16 v[78:81], v[130:133], v[210:213], v[78:81]
	v_mfma_f32_16x16x32_bf16 v[74:77], v[152:155], v[210:213], v[74:77]
	v_mfma_f32_16x16x32_bf16 v[126:129], v[134:137], v[164:167], v[126:129]
	v_mfma_f32_16x16x32_bf16 v[122:125], v[156:159], v[164:167], v[122:125]
	v_mfma_f32_16x16x32_bf16 v[110:113], v[134:137], v[198:201], v[110:113]
	v_mfma_f32_16x16x32_bf16 v[106:109], v[156:159], v[198:201], v[106:109]
	v_mfma_f32_16x16x32_bf16 v[94:97], v[134:137], v[206:209], v[94:97]
	v_mfma_f32_16x16x32_bf16 v[90:93], v[156:159], v[206:209], v[90:93]
	v_mfma_f32_16x16x32_bf16 v[78:81], v[134:137], v[214:217], v[78:81]
	v_mfma_f32_16x16x32_bf16 v[74:77], v[156:159], v[214:217], v[74:77]
	v_mfma_f32_16x16x32_bf16 v[118:121], v[218:221], v[160:163], v[118:121]
	v_mfma_f32_16x16x32_bf16 v[114:117], v[226:229], v[160:163], v[114:117]
	v_mfma_f32_16x16x32_bf16 v[102:105], v[218:221], v[194:197], v[102:105]
	v_mfma_f32_16x16x32_bf16 v[98:101], v[226:229], v[194:197], v[98:101]
	v_mfma_f32_16x16x32_bf16 v[86:89], v[218:221], v[202:205], v[86:89]
	v_mfma_f32_16x16x32_bf16 v[82:85], v[226:229], v[202:205], v[82:85]
	v_mfma_f32_16x16x32_bf16 v[70:73], v[218:221], v[210:213], v[70:73]
	v_mfma_f32_16x16x32_bf16 v[66:69], v[226:229], v[210:213], v[66:69]
	v_mfma_f32_16x16x32_bf16 v[118:121], v[222:225], v[164:167], v[118:121]
	v_mfma_f32_16x16x32_bf16 v[114:117], v[230:233], v[164:167], v[114:117]
	v_mfma_f32_16x16x32_bf16 v[102:105], v[222:225], v[198:201], v[102:105]
	v_mfma_f32_16x16x32_bf16 v[98:101], v[230:233], v[198:201], v[98:101]
	v_mfma_f32_16x16x32_bf16 v[86:89], v[222:225], v[206:209], v[86:89]
	v_mfma_f32_16x16x32_bf16 v[82:85], v[230:233], v[206:209], v[82:85]
	v_mfma_f32_16x16x32_bf16 v[70:73], v[222:225], v[214:217], v[70:73]
	v_mfma_f32_16x16x32_bf16 v[66:69], v[230:233], v[214:217], v[66:69]
	s_setprio 0
	s_barrier
	ds_read_b128 v[160:163], v193 offset:16384
	ds_read_b128 v[164:167], v193 offset:17408
	ds_read_b128 v[194:197], v193 offset:18432
	ds_read_b128 v[198:201], v193 offset:19456
	ds_read_b128 v[202:205], v193 offset:20480
	ds_read_b128 v[206:209], v193 offset:21504
	ds_read_b128 v[210:213], v193 offset:22528
	ds_read_b128 v[214:217], v193 offset:23552
	v_lshl_add_u64 v[168:169], s[20:21], 0, v[138:139]
	s_mov_b32 m0, s43
	v_lshl_add_u64 v[234:235], s[20:21], 0, v[140:141]
	global_load_lds_dwordx4 v[168:169], off
	s_add_i32 m0, s43, 0x2000
	s_nop 0
	global_load_lds_dwordx4 v[234:235], off
	s_mov_b32 m0, s19
	v_lshl_add_u64 v[236:237], s[22:23], 0, v[138:139]
	global_load_lds_dwordx4 v[236:237], off
	v_lshl_add_u64 v[238:239], s[22:23], 0, v[140:141]
	s_mov_b32 m0, s27
	s_nop 0
	global_load_lds_dwordx4 v[238:239], off
	s_add_u32 s44, s20, 0x40000
	s_addc_u32 s45, s21, 0
	s_add_i32 s43, s46, s26
	v_lshl_add_u64 v[240:241], s[44:45], 0, v[138:139]
	s_mov_b32 m0, s43
	s_nop 0
	global_load_lds_dwordx4 v[240:241], off
	v_lshl_add_u64 v[240:241], s[44:45], 0, v[140:141]
	s_add_i32 m0, s43, 0x2000
	s_nop 0
	global_load_lds_dwordx4 v[240:241], off
	s_cmp_eq_u32 s42, -2
	s_cbranch_scc0 .Lwin_b0_strict
	s_cmp_gt_u32 s38, 1
	s_cbranch_scc1 .Lwin_b0_relaxed
